# dense attention loops unrolled by 2 (one copy per LDS stage): no per-iteration stage toggling (2 VALU + 5 SALU fewer per iteration); placement pads keep 8-byte phase
# speedup vs baseline: 1.0001x; 1.0001x over previous
; template <int DQK, bool BAND, int QT> ...
;     ...
;   const int tid = tid_(), lane = tid & 63, w = tid >> 6, h = lane >> 5, ql = lane & 31;
;   float* bias_l = (float*)(lds + 2 * ST);
;   if (BAND) { if (tid < 129) bias_l[tid] = bias_g[tid]; }
;   bf16x8 qf[QT][NKS];
; #pragma unroll
;   for (int qt = 0; qt < QT; ++qt)
; #pragma unroll
;     for (int ks = 0; ks < NKS; ++ks) qf[qt][ks] = *(const bf16x8*)(Q + (size_t)(w * WQ + qt * 32 + ql) * DQK + ks * 16 + h * 8);
;   f32x16 o[2][QT];
; #pragma unroll
;   for (int a = 0; a < 2; ++a)
; #pragma unroll
;     for (int b = 0; b < QT; ++b)
; #pragma unroll
;       for (int r = 0; r < 16; ++r) o[a][b][r] = 0.f;
;   float m[QT], l[QT];
; #pragma unroll
;   for (int qt = 0; qt < QT; ++qt) { m[qt] = -1e30f; l[qt] = 0.f; }
;   u32x4 rk[NKL], rv[2];
;   const int vrow0 = tid >> 3, vch = tid & 7;
;   unsigned klds[NKL];
; #pragma unroll
;   for (int i = 0; i < NKL; ++i) { const int idx = tid + i * 256, kr = idx / KV4, kc = idx - kr * KV4; klds[i] = kr * KROW + kc * 16; }
;   const unsigned koff0 = (unsigned)tid * 16u;
;   const unsigned voff0 = (unsigned)(vrow0 * ldv + vch * 8) * 2u, vstep = (unsigned)(32 * ldv) * 2u;
;   const unsigned vlds0 = KST + vrow0 * LROW + vch * 16;
;   auto gload = [&](int kt) {
;     const char* kb = (const char*)Kp + (size_t)kt * (DQK * 2);
;     const char* vb = (const char*)Vt + (size_t)kt * 2;
; #pragma unroll
;     for (int i = 0; i < NKL; ++i) rk[i] = *(const u32x4*)(kb + (koff0 + i * 4096u));
; #pragma unroll
; DI void phase_attn(const Ctx& c) {
;     ...
;       const int i2 = item - n_mla;
;       const int hq = i2 & 7, rest = i2 >> 3, seq = rest / nqb, qb = rest - seq * nqb;
;       const size_t hs = (size_t)(seq * 8 + hq) * S, ks = (size_t)(seq * 2 + (hq >> 2)) * S;
;       if (ATT_PIPE) attn_dense<64>(wsb(c, OFF_QC) + (hs + qb * QBLK) * 64, wsb(c, OFF_KC) + ks * 64, wsb(c, OFF_VTC) + (size_t)(seq * 2 + (hq >> 2)) * 64 * (S + 64), S + 64,
;                      S, 0.125f * LOG2E, wsb(c, OFF_OC) + ((size_t)seq * S + qb * QBLK) * LDO + hq * 64, LDO, c.lds);
;       else attn_item<64, false, AQT>(wsb(c, OFF_QC) + (hs + qb * QBLK) * 64, wsb(c, OFF_KC) + ks * 64, wsb(c, OFF_VTC) + (size_t)(seq * 2 + (hq >> 2)) * 64 * (S + 64), S + 64,
;                      0, S, 0, nullptr, 0.125f * LOG2E, wsb(c, OFF_OC) + ((size_t)seq * S + qb * QBLK) * LDO + hq * 64, LDO, nullptr, 0, c.lds);
.LBB0_826:
	s_and_b64 vcc, exec, s[0:1]
	s_cbranch_vccz .LBB0_838
	v_readlane_b32 s0, v249, 58
	s_sub_i32 s0, s26, s0
	s_ashr_i32 s1, s0, 3
	s_ashr_i32 s7, s0, 31
	s_abs_i32 s0, s1
	v_readlane_b32 s2, v248, 3
	s_mul_hi_u32 s2, s0, s2
	v_readlane_b32 s5, v248, 2
	s_mul_i32 s3, s2, s5
	s_sub_i32 s0, s0, s3
	s_add_i32 s3, s2, 1
	s_sub_i32 s4, s0, s5
	s_cmp_ge_u32 s0, s5
	s_cselect_b32 s2, s3, s2
	s_cselect_b32 s0, s4, s0
	s_add_i32 s3, s2, 1
	s_cmp_ge_u32 s0, s5
	s_cselect_b32 s0, s3, s2
	s_xor_b32 s40, s0, s7
	s_sub_i32 s0, s40, s7
	s_lshl_b32 s2, s0, s60
	s_sub_i32 s1, s1, s2
	s_lshl_b32 s2, s0, 3
	v_readlane_b32 s3, v249, 31
	s_or_b32 s2, s2, s3
	s_lshl_b32 s4, s0, 1
	v_readlane_b32 s41, v250, 44
	s_ashr_i32 s3, s2, 31
	s_or_b32 s26, s4, s41
	s_lshl_b32 s4, s1, 8
	s_lshl_b64 s[2:3], s[2:3], s20
	s_ashr_i32 s27, s26, 31
	s_ashr_i32 s5, s4, 31
	s_add_u32 s2, s2, s4
	s_addc_u32 s3, s3, s5
	s_lshl_b64 s[2:3], s[2:3], 7
	v_readlane_b32 s1, v250, 53
	s_add_u32 s34, s1, s2
	v_readlane_b32 s1, v250, 54
	s_addc_u32 s35, s1, s3
	v_readlane_b32 s1, v248, 1
	s_lshl_b64 s[2:3], s[26:27], s1
	v_readlane_b32 s1, v250, 55
	s_add_u32 s38, s1, s2
	v_readlane_b32 s1, v250, 56
	v_mov_b32_e32 v5, v199
	s_addc_u32 s39, s1, s3
	v_readlane_b32 s1, v249, 61
	v_readlane_b32 s6, v249, 63
	v_lshlrev_b32_e32 v2, 4, v5
	v_ashrrev_i32_e32 v18, 3, v5
	s_mul_hi_i32 s27, s26, s1
	s_mul_i32 s26, s26, s1
	v_and_b32_e32 v4, 0x70, v2
	v_mul_lo_u32 v0, v18, s6
	v_bfe_u32 v196, v5, 5, 1
	v_and_b32_e32 v180, 0xffffffdf, v5
	s_lshl_b64 s[26:27], s[26:27], 1
	v_readlane_b32 s42, v250, 28
	v_or_b32_e32 v6, v4, v0
	s_waitcnt vmcnt(16)
	v_or_b32_e32 v178, 32, v5
	v_lshlrev_b32_e32 v0, 4, v196
	v_ashrrev_i32_e32 v181, 31, v180
	v_readlane_b32 s43, v250, 29
	s_add_u32 s26, s42, s26
	v_ashrrev_i32_e32 v179, 31, v178
	v_lshlrev_b64 v[12:13], 7, v[180:181]
	v_lshl_add_u64 v[16:17], s[34:35], 0, v[0:1]
	s_addc_u32 s27, s43, s27
	v_lshlrev_b64 v[14:15], 7, v[178:179]
	v_lshl_add_u64 v[12:13], v[16:17], 0, v[12:13]
	v_add_u32_e32 v8, 0x1000, v2
	global_load_dwordx4 v[130:133], v2, s[38:39]
	global_load_dwordx4 v[134:137], v8, s[38:39]
	v_add_u32_e32 v10, s1, v6
	global_load_dwordx4 v[138:141], v6, s[26:27]
	global_load_dwordx4 v[142:145], v10, s[26:27]
	v_lshl_add_u64 v[14:15], v[16:17], 0, v[14:15]
	global_load_dwordx4 v[146:149], v[12:13], off
	global_load_dwordx4 v[150:153], v[12:13], off offset:32
	global_load_dwordx4 v[154:157], v[12:13], off offset:64
	global_load_dwordx4 v[158:161], v[12:13], off offset:96
	global_load_dwordx4 v[162:165], v[14:15], off
	global_load_dwordx4 v[166:169], v[14:15], off offset:32
	global_load_dwordx4 v[170:173], v[14:15], off offset:64
	global_load_dwordx4 v[174:177], v[14:15], off offset:96
	v_ashrrev_i32_e32 v19, 31, v5
	v_add_u32_e32 v20, 0x100, v5
	v_lshrrev_b32_e32 v13, 29, v19
	v_ashrrev_i32_e32 v14, 31, v20
	v_add_u32_e32 v13, v5, v13
	v_lshrrev_b32_e32 v14, 29, v14
	v_mad_u64_u32 v[182:183], s[26:27], v18, s16, v[4:5]
	v_ashrrev_i32_e32 v13, 3, v13
	v_add_u32_e32 v4, v20, v14
	v_lshlrev_b32_e32 v16, 7, v13
	v_ashrrev_i32_e32 v17, 3, v4
	v_lshlrev_b32_e32 v15, 4, v20
	v_sub_u32_e32 v4, v2, v16
	v_lshlrev_b32_e32 v16, 7, v17
	v_mad_u64_u32 v[184:185], s[26:27], v13, s16, v[4:5]
	v_sub_u32_e32 v4, v15, v16
	v_mad_u64_u32 v[186:187], s[26:27], v17, s16, v[4:5]
	s_lshl_b32 s26, s40, 1
	s_or_b32 s26, s41, s26
	s_lshl_b32 s7, s7, 1
	s_sub_i32 s7, s26, s7
	v_readlane_b32 s26, v248, 4
	v_and_b32_e32 v12, 31, v5
	v_add_u32_e32 v4, 0, v184
	s_mul_hi_i32 s27, s26, s7
	s_mul_i32 s7, s26, s7
	v_add_u32_e32 v14, 0, v182
	v_add_u32_e32 v13, 0, v186
	v_mul_u32_u24_e32 v183, 0x90, v12
	v_lshlrev_b32_e32 v12, 1, v5
	s_add_u32 s26, s7, 0x179d5980
	s_waitcnt vmcnt(11)
	ds_write_b128 v4, v[130:133]
	s_waitcnt vmcnt(10)
	ds_write_b128 v13, v[134:137]
	s_waitcnt vmcnt(9)
	ds_write_b128 v14, v[138:141] offset:9216
	s_waitcnt vmcnt(8)
	ds_write_b128 v14, v[142:145] offset:13824
	v_and_b32_e32 v4, 19, v5
	v_lshrrev_b32_e32 v5, 1, v5
	v_and_b32_e32 v12, 8, v12
	v_and_b32_e32 v5, 4, v5
	s_addc_u32 s27, s27, 0
	v_or3_b32 v4, v4, v12, v5
	v_cmp_lt_i32_e32 vcc, v221, v220
	s_add_u32 s2, s2, 0x175d7900
	v_mov_b32_e32 v3, v1
	v_mov_b32_e32 v9, v1
	v_mov_b32_e32 v7, v1
	v_mov_b32_e32 v11, v1
	v_mul_u32_u24_e32 v185, 0x90, v4
	v_cndmask_b32_e32 v4, v219, v221, vcc
	s_addc_u32 s3, s3, 0
	v_mov_b32_e32 v50, v1
	v_mov_b32_e32 v51, v1
	v_lshlrev_b32_e32 v179, 2, v4
	v_lshl_add_u64 v[188:189], s[26:27], 0, v[6:7]
	v_lshl_add_u64 v[190:191], s[26:27], 0, v[10:11]
	v_lshl_add_u64 v[192:193], s[2:3], 0, v[2:3]
	v_lshl_add_u64 v[194:195], s[2:3], 0, v[8:9]
	v_mov_b32_e32 v52, v1
	v_mov_b32_e32 v53, v1
	v_mov_b32_e32 v54, v1
	v_mov_b32_e32 v55, v1
	v_mov_b32_e32 v56, v1
	v_mov_b32_e32 v57, v1
	v_mov_b32_e32 v58, v1
	v_mov_b32_e32 v59, v1
	v_mov_b32_e32 v60, v1
	v_mov_b32_e32 v61, v1
	v_mov_b32_e32 v62, v1
	v_mov_b32_e32 v63, v1
	v_mov_b32_e32 v64, v1
	v_mov_b32_e32 v65, v1
	v_mov_b64_e32 v[18:19], v[50:51]
	v_mov_b64_e32 v[34:35], v[50:51]
	v_mov_b64_e32 v[2:3], v[50:51]
	s_mov_b32 s1, 0
	s_mov_b32 s6, 64
	v_mov_b32_e32 v197, 0xf149f2ca
	v_mov_b32_e32 v187, 0
	v_mov_b32_e32 v181, 0
	v_mov_b32_e32 v202, 0xf149f2ca
	v_mov_b64_e32 v[20:21], v[52:53]
	v_mov_b64_e32 v[22:23], v[54:55]
	v_mov_b64_e32 v[24:25], v[56:57]
	v_mov_b64_e32 v[26:27], v[58:59]
	v_mov_b64_e32 v[28:29], v[60:61]
	v_mov_b64_e32 v[30:31], v[62:63]
	v_mov_b64_e32 v[32:33], v[64:65]
	v_mov_b64_e32 v[36:37], v[52:53]
	v_mov_b64_e32 v[38:39], v[54:55]
	v_mov_b64_e32 v[40:41], v[56:57]
	v_mov_b64_e32 v[42:43], v[58:59]
; #define MFMA(a, b, c) __builtin_amdgcn_mfma_f32_32x32x16_bf16((a), (b), (c), 0, 0, 0)
; template <int DQK, bool BAND, int QT> ...
;     ...
;   const int vrow0 = tid >> 3, vch = tid & 7;
;   unsigned klds[NKL];
; #pragma unroll
;   for (int i = 0; i < NKL; ++i) { const int idx = tid + i * 256, kr = idx / KV4, kc = idx - kr * KV4; klds[i] = kr * KROW + kc * 16; }
;   const unsigned koff0 = (unsigned)tid * 16u;
;   const unsigned voff0 = (unsigned)(vrow0 * ldv + vch * 8) * 2u, vstep = (unsigned)(32 * ldv) * 2u;
;   const unsigned vlds0 = KST + vrow0 * LROW + vch * 16;
;   auto gload = [&](int kt) {
;     const char* kb = (const char*)Kp + (size_t)kt * (DQK * 2);
;     const char* vb = (const char*)Vt + (size_t)kt * 2;
; #pragma unroll
;     for (int i = 0; i < NKL; ++i) rk[i] = *(const u32x4*)(kb + (koff0 + i * 4096u));
; #pragma unroll
;     for (int i = 0; i < 2; ++i) rv[i] = *(const u32x4*)(vb + (voff0 + i * vstep));
;   };
;   auto lstore = [&](char* st) {
; #pragma unroll
;     for (int i = 0; i < NKL; ++i) *(u32x4*)(st + klds[i]) = rk[i];
; #pragma unroll
;     for (int i = 0; i < 2; ++i) *(u32x4*)(st + vlds0 + i * 32 * LROW) = rv[i];
;   };
;   gload(kbeg);
;   lstore(lds);
;   __syncthreads();
;   const int pr = (ql & ~12) | ((ql & 4) << 1) | ((ql & 8) >> 1);
;   const int k_rd = pr * KROW + h * 16;
;   const int v_rd = KST + ql * LROW + h * 16;
;   const int qw0 = q0 + w * WQ;
;   int it = 0;
;   for (int kt = kbeg; kt < kend; kt += 64, ++it) {
;     const char* st = lds + (it & 1) * ST;
;     const bool more = (kt + 64 < kend);
;     if (more) gload(kt + 64);
;     bool need = true;
;     if (BAND) need = (kt + 63 >= qw0 - 64) && (kt <= qw0 + WQ - 1 + 64);
;     if (need) {
;       f32x16 s[2][QT];
; #pragma unroll
;       for (int a = 0; a < 2; ++a)
; #pragma unroll
;         for (int b = 0; b < QT; ++b)
; #pragma unroll
;           for (int r = 0; r < 16; ++r) s[a][b][r] = 0.f;
; #pragma unroll
;       for (int ks = 0; ks < NKS; ++ks) {
;         const bf16x8 k0 = *(const bf16x8*)(st + k_rd + ks * 32);
;         const bf16x8 k1 = *(const bf16x8*)(st + k_rd + 32 * KROW + ks * 32);
; #pragma unroll
;         for (int qt = 0; qt < QT; ++qt) {
;           s[0][qt] = MFMA(k0, qf[qt][ks], s[0][qt]);
	v_mov_b64_e32 v[44:45], v[60:61]
	v_mov_b64_e32 v[46:47], v[62:63]
	v_mov_b64_e32 v[48:49], v[64:65]
	v_mov_b64_e32 v[4:5], v[52:53]
	v_mov_b64_e32 v[6:7], v[54:55]
	v_mov_b64_e32 v[8:9], v[56:57]
	v_mov_b64_e32 v[10:11], v[58:59]
	v_mov_b64_e32 v[12:13], v[60:61]
	v_mov_b64_e32 v[14:15], v[62:63]
	v_mov_b64_e32 v[16:17], v[64:65]
	v_add_u32_e32 v185, v185, v0
	v_add_u32_e32 v183, v183, v0
	v_mbcnt_lo_u32_b32 v254, -1, 0
	v_mbcnt_hi_u32_b32 v254, -1, v254
	v_and_b32_e32 v255, 15, v254
	v_lshrrev_b32_e32 v253, 4, v254
	v_and_b32_e32 v253, 1, v253
	v_cmp_eq_u32_e32 vcc, v255, v253
	v_mov_b32_e32 v253, 0x3f803f80
	s_nop 1
	v_cndmask_b32_e32 v244, 0, v253, vcc
	v_mov_b32_e32 v245, v244
	v_mov_b32_e32 v246, v244
	v_mov_b32_e32 v247, v244
	v_mov_b32_e32 v236, 0
	v_mov_b32_e32 v237, 0
	v_mov_b32_e32 v238, 0
	v_mov_b32_e32 v239, 0
	v_mov_b32_e32 v240, 0
	v_mov_b32_e32 v241, 0
	v_mov_b32_e32 v242, 0
	v_mov_b32_e32 v243, 0
	v_readfirstlane_b32 s38, v199
	s_lshr_b32 s38, s38, 6
	s_lshl_b32 s39, s38, 10
	v_readlane_b32 s25, v249, 63
	v_mov_b32_e32 v253, v199
	v_mul_u32_u24_e32 v254, 0x1c72, v253
	v_lshrrev_b32_e32 v254, 16, v254
	v_mul_u32_u24_e32 v255, 9, v254
	v_sub_u32_e32 v255, v253, v255
	v_min_u32_e32 v255, 7, v255
	v_mul_u32_u24_e32 v254, 0x80, v254
	v_lshl_add_u32 v130, v255, 4, v254
	v_add_u32_e32 v253, 0x100, v199
	v_mul_u32_u24_e32 v254, 0x1c72, v253
	v_lshrrev_b32_e32 v254, 16, v254
	v_mul_u32_u24_e32 v255, 9, v254
	v_sub_u32_e32 v255, v253, v255
	v_min_u32_e32 v255, 7, v255
	v_mul_u32_u24_e32 v254, 0x80, v254
	v_lshl_add_u32 v131, v255, 4, v254
	v_mov_b32_e32 v253, v199
	v_mul_u32_u24_e32 v254, 0x1c72, v253
	v_lshrrev_b32_e32 v254, 16, v254
	v_mul_u32_u24_e32 v255, 9, v254
	v_sub_u32_e32 v255, v253, v255
	v_min_u32_e32 v255, 7, v255
	v_mul_lo_u32 v254, v254, s25
	v_lshl_add_u32 v132, v255, 4, v254
	v_add_u32_e32 v253, 0x100, v199
	v_mul_u32_u24_e32 v254, 0x1c72, v253
	v_lshrrev_b32_e32 v254, 16, v254
	v_mul_u32_u24_e32 v255, 9, v254
	v_sub_u32_e32 v255, v253, v255
	v_min_u32_e32 v255, 7, v255
	v_mul_lo_u32 v254, v254, s25
	v_lshl_add_u32 v133, v255, 4, v254
	v_add_u32_e32 v253, 0x200, v199
	v_mul_u32_u24_e32 v254, 0x1c72, v253
	v_lshrrev_b32_e32 v254, 16, v254
	v_mul_u32_u24_e32 v255, 9, v254
	v_sub_u32_e32 v255, v253, v255
	v_min_u32_e32 v255, 7, v255
	v_mul_u32_u24_e32 v254, 0x80, v254
	v_lshl_add_u32 v134, v255, 4, v254
	v_add_u32_e32 v253, 0x1c0, v199
	v_mul_u32_u24_e32 v254, 0x1c72, v253
	v_lshrrev_b32_e32 v254, 16, v254
	v_mul_u32_u24_e32 v255, 9, v254
	v_sub_u32_e32 v255, v253, v255
	v_min_u32_e32 v255, 7, v255
	v_mul_lo_u32 v254, v254, s25
	v_lshl_add_u32 v135, v255, 4, v254
	v_cmp_gt_u32_e32 vcc, 64, v199
	s_nop 1
	v_cndmask_b32_e32 v134, v135, v134, vcc
	v_readfirstlane_b32 s34, v192
	v_readfirstlane_b32 s35, v193
	s_add_u32 s34, s34, s94
	s_addc_u32 s35, s35, s95
	s_sub_u32 s34, s34, s39
	s_subb_u32 s35, s35, 0
	v_readfirstlane_b32 s26, v188
	v_readfirstlane_b32 s27, v189
	s_add_u32 s26, s26, s94
	s_addc_u32 s27, s27, s95
	s_mul_i32 s42, s38, s25
	s_lshl_b32 s42, s42, 3
	s_sub_u32 s26, s26, s42
	s_subb_u32 s27, s27, 0
	v_mov_b32_e32 v136, 0xf149f2ca
	v_mov_b32_e32 v137, 0xf149f2ca
	v_mov_b32_e32 v138, 0
	v_mov_b32_e32 v139, 0
	v_add_u32_e32 v140, 0x4800, v185
	v_add_u32_e32 v141, 0x4800, v183
	s_waitcnt vmcnt(0) lgkmcnt(0)
	s_barrier
.Lgqa_top:
	ds_read_b128 v[206:209], v185
	ds_read_b128 v[210:213], v185 offset:4608
	ds_read_b128 v[214:217], v185 offset:32
	ds_read_b128 v[232:235], v185 offset:4640
	s_waitcnt lgkmcnt(3)
	v_mfma_f32_32x32x16_bf16 v[82:97], v[206:209], v[146:149], 0
	v_mfma_f32_32x32x16_bf16 v[114:129], v[206:209], v[162:165], 0
	ds_read_b128 v[206:209], v185 offset:64
	s_waitcnt lgkmcnt(3)
	v_mfma_f32_32x32x16_bf16 v[66:81], v[210:213], v[146:149], 0
	v_mfma_f32_32x32x16_bf16 v[98:113], v[210:213], v[162:165], 0
	ds_read_b128 v[210:213], v185 offset:4672
	s_waitcnt lgkmcnt(3)
	v_mfma_f32_32x32x16_bf16 v[82:97], v[214:217], v[150:153], v[82:97]
	v_mfma_f32_32x32x16_bf16 v[114:129], v[214:217], v[166:169], v[114:129]
	ds_read_b128 v[214:217], v185 offset:96
	s_waitcnt lgkmcnt(3)
	v_mfma_f32_32x32x16_bf16 v[66:81], v[232:235], v[150:153], v[66:81]
	v_mfma_f32_32x32x16_bf16 v[98:113], v[232:235], v[166:169], v[98:113]
	ds_read_b128 v[232:235], v185 offset:4704
	s_waitcnt lgkmcnt(3)
	v_mfma_f32_32x32x16_bf16 v[82:97], v[206:209], v[154:157], v[82:97]
	v_mfma_f32_32x32x16_bf16 v[114:129], v[206:209], v[170:173], v[114:129]
	s_waitcnt lgkmcnt(2)
	v_mfma_f32_32x32x16_bf16 v[66:81], v[210:213], v[154:157], v[66:81]
	v_mfma_f32_32x32x16_bf16 v[98:113], v[210:213], v[170:173], v[98:113]
	s_waitcnt lgkmcnt(1)
	v_mfma_f32_32x32x16_bf16 v[82:97], v[214:217], v[158:161], v[82:97]
	v_mfma_f32_32x32x16_bf16 v[114:129], v[214:217], v[174:177], v[114:129]
	s_waitcnt lgkmcnt(0)
	v_mfma_f32_32x32x16_bf16 v[66:81], v[232:235], v[158:161], v[66:81]
	v_mfma_f32_32x32x16_bf16 v[98:113], v[232:235], v[174:177], v[98:113]
	s_cmp_lt_u32 s6, s19
	s_cbranch_scc0 .Lgqa_dma_noload
	s_add_u32 s2, s39, 0x4800
	s_nop 0
	s_mov_b32 m0, s2
	s_add_u32 s3, s2, 0x1000
	global_load_lds_dwordx4 v130, s[34:35]
	s_mov_b32 m0, s3
	s_add_u32 s3, s2, 0x2400
	global_load_lds_dwordx4 v131, s[34:35]
	s_mov_b32 m0, s3
	s_add_u32 s3, s2, 0x3400
	global_load_lds_dwordx4 v132, s[26:27]
	s_mov_b32 m0, s3
	s_sub_u32 s3, s2, s39
	global_load_lds_dwordx4 v133, s[26:27]
	s_cmp_gt_u32 s38, 1
	s_cbranch_scc1 .Lgqa_dma_x2
	s_cmp_eq_u32 s38, 0
	s_cbranch_scc0 .Lgqa_dma_x1
	s_add_u32 m0, s3, 0x2000
	s_nop 0
	global_load_lds_dwordx4 v134, s[34:35]
	s_branch .Lgqa_dma_x2

; #define MFMA(a, b, c) __builtin_amdgcn_mfma_f32_32x32x16_bf16((a), (b), (c), 0, 0, 0)
; DI unsigned pk2(float a, float b) { f32x2 v = {a, b}; bf16x2_t r = __builtin_convertvector(v, bf16x2_t); return __builtin_bit_cast(unsigned, r); }
; template <int DQK, bool BAND, int QT> ...
;     ...
;         const float mc = -m[qt] * cc;
;         float ls = 0.f;
; #pragma unroll
;         for (int a = 0; a < 2; ++a) {
; #pragma unroll
;           for (int r = 0; r < 16; ++r) { const float pv = __builtin_amdgcn_exp2f(fmaf(s[a][qt][r], cc, mc)); s[a][qt][r] = pv; ls += pv; }
; #pragma unroll
;           for (int s2 = 0; s2 < 2; ++s2) {
;             u32x4 pk;
;             pk.x = pk2(s[a][qt][8 * s2 + 0], s[a][qt][8 * s2 + 1]);
;             pk.y = pk2(s[a][qt][8 * s2 + 2], s[a][qt][8 * s2 + 3]);
;             pk.z = pk2(s[a][qt][8 * s2 + 4], s[a][qt][8 * s2 + 5]);
;             pk.w = pk2(s[a][qt][8 * s2 + 6], s[a][qt][8 * s2 + 7]);
;             pf[qt][a * 2 + s2] = __builtin_bit_cast(bf16x8, pk);
;           }
;         }
;         l[qt] += ls;
;       }
;       __builtin_amdgcn_s_setprio(0);
;       if (more) lstore(lds + ((it + 1) & 1) * ST);
; #pragma unroll
;       for (int ks = 0; ks < 4; ++ks) {
;         const bf16x8 v0 = *(const bf16x8*)(st + v_rd + ks * 32);
;         const bf16x8 v1 = *(const bf16x8*)(st + v_rd + 32 * LROW + ks * 32);
; #pragma unroll
;         for (int qt = 0; qt < QT; ++qt) {
;           o[0][qt] = MFMA(v0, pf[qt][ks], o[0][qt]);
;           o[1][qt] = MFMA(v1, pf[qt][ks], o[1][qt]);
;         }
;       }
.Lgqa_nr1:
	v_fmamk_f32 v82, v82, 0x3e38aa3b, v138
	v_fmamk_f32 v114, v114, 0x3e38aa3b, v139
	v_fmamk_f32 v83, v83, 0x3e38aa3b, v138
	v_fmamk_f32 v115, v115, 0x3e38aa3b, v139
	v_fmamk_f32 v84, v84, 0x3e38aa3b, v138
	v_fmamk_f32 v116, v116, 0x3e38aa3b, v139
	v_fmamk_f32 v85, v85, 0x3e38aa3b, v138
	v_fmamk_f32 v117, v117, 0x3e38aa3b, v139
	v_fmamk_f32 v86, v86, 0x3e38aa3b, v138
	v_fmamk_f32 v118, v118, 0x3e38aa3b, v139
	v_fmamk_f32 v87, v87, 0x3e38aa3b, v138
	v_fmamk_f32 v119, v119, 0x3e38aa3b, v139
	v_fmamk_f32 v88, v88, 0x3e38aa3b, v138
	v_fmamk_f32 v120, v120, 0x3e38aa3b, v139
	v_fmamk_f32 v89, v89, 0x3e38aa3b, v138
	v_fmamk_f32 v121, v121, 0x3e38aa3b, v139
	v_exp_f32_e32 v82, v82
	v_exp_f32_e32 v114, v114
	v_exp_f32_e32 v83, v83
	v_exp_f32_e32 v115, v115
	v_exp_f32_e32 v84, v84
	v_exp_f32_e32 v116, v116
	v_exp_f32_e32 v85, v85
	v_exp_f32_e32 v117, v117
	v_exp_f32_e32 v86, v86
	v_exp_f32_e32 v118, v118
	v_exp_f32_e32 v87, v87
	v_exp_f32_e32 v119, v119
	v_exp_f32_e32 v88, v88
	v_exp_f32_e32 v120, v120
	v_exp_f32_e32 v89, v89
	v_exp_f32_e32 v121, v121
	v_fmamk_f32 v90, v90, 0x3e38aa3b, v138
	v_fmamk_f32 v122, v122, 0x3e38aa3b, v139
	v_fmamk_f32 v91, v91, 0x3e38aa3b, v138
	v_fmamk_f32 v123, v123, 0x3e38aa3b, v139
	v_fmamk_f32 v92, v92, 0x3e38aa3b, v138
	v_fmamk_f32 v124, v124, 0x3e38aa3b, v139
	v_fmamk_f32 v93, v93, 0x3e38aa3b, v138
	v_fmamk_f32 v125, v125, 0x3e38aa3b, v139
	v_fmamk_f32 v94, v94, 0x3e38aa3b, v138
	v_fmamk_f32 v126, v126, 0x3e38aa3b, v139
	v_fmamk_f32 v95, v95, 0x3e38aa3b, v138
	v_fmamk_f32 v127, v127, 0x3e38aa3b, v139
	v_fmamk_f32 v96, v96, 0x3e38aa3b, v138
	v_fmamk_f32 v128, v128, 0x3e38aa3b, v139
	v_fmamk_f32 v97, v97, 0x3e38aa3b, v138
	v_fmamk_f32 v129, v129, 0x3e38aa3b, v139
	v_exp_f32_e32 v90, v90
	v_exp_f32_e32 v122, v122
	v_exp_f32_e32 v91, v91
	v_exp_f32_e32 v123, v123
	v_exp_f32_e32 v92, v92
	v_exp_f32_e32 v124, v124
	v_exp_f32_e32 v93, v93
	v_exp_f32_e32 v125, v125
	v_exp_f32_e32 v94, v94
	v_exp_f32_e32 v126, v126
	v_exp_f32_e32 v95, v95
	v_exp_f32_e32 v127, v127
	v_exp_f32_e32 v96, v96
	v_exp_f32_e32 v128, v128
	v_exp_f32_e32 v97, v97
	v_exp_f32_e32 v129, v129
	v_cvt_pk_bf16_f32 v82, v82, v83
	v_cvt_pk_bf16_f32 v114, v114, v115
	v_cvt_pk_bf16_f32 v83, v84, v85
	v_cvt_pk_bf16_f32 v115, v116, v117
	v_cvt_pk_bf16_f32 v84, v86, v87
	v_cvt_pk_bf16_f32 v116, v118, v119
	v_cvt_pk_bf16_f32 v85, v88, v89
	v_cvt_pk_bf16_f32 v117, v120, v121
	v_fmamk_f32 v66, v66, 0x3e38aa3b, v138
	v_fmamk_f32 v98, v98, 0x3e38aa3b, v139
	v_fmamk_f32 v67, v67, 0x3e38aa3b, v138
	v_fmamk_f32 v99, v99, 0x3e38aa3b, v139
	v_fmamk_f32 v68, v68, 0x3e38aa3b, v138
	v_fmamk_f32 v100, v100, 0x3e38aa3b, v139
	v_fmamk_f32 v69, v69, 0x3e38aa3b, v138
	v_fmamk_f32 v101, v101, 0x3e38aa3b, v139
	v_fmamk_f32 v70, v70, 0x3e38aa3b, v138
	v_fmamk_f32 v102, v102, 0x3e38aa3b, v139
	v_fmamk_f32 v71, v71, 0x3e38aa3b, v138
	v_fmamk_f32 v103, v103, 0x3e38aa3b, v139
	v_fmamk_f32 v72, v72, 0x3e38aa3b, v138
	v_fmamk_f32 v104, v104, 0x3e38aa3b, v139
	v_fmamk_f32 v73, v73, 0x3e38aa3b, v138
	v_fmamk_f32 v105, v105, 0x3e38aa3b, v139
	v_exp_f32_e32 v66, v66
	v_exp_f32_e32 v98, v98
	v_exp_f32_e32 v67, v67
	v_exp_f32_e32 v99, v99
	v_exp_f32_e32 v68, v68
	v_exp_f32_e32 v100, v100
	v_exp_f32_e32 v69, v69
	v_exp_f32_e32 v101, v101
	v_exp_f32_e32 v70, v70
	v_exp_f32_e32 v102, v102
	v_exp_f32_e32 v71, v71
	v_exp_f32_e32 v103, v103
	v_exp_f32_e32 v72, v72
	v_exp_f32_e32 v104, v104
	v_exp_f32_e32 v73, v73
	v_exp_f32_e32 v105, v105
	v_cvt_pk_bf16_f32 v90, v90, v91
	v_cvt_pk_bf16_f32 v122, v122, v123
	v_cvt_pk_bf16_f32 v91, v92, v93
	v_cvt_pk_bf16_f32 v123, v124, v125
	v_cvt_pk_bf16_f32 v92, v94, v95
	v_cvt_pk_bf16_f32 v124, v126, v127
	v_cvt_pk_bf16_f32 v93, v96, v97
	v_cvt_pk_bf16_f32 v125, v128, v129
	v_fmamk_f32 v74, v74, 0x3e38aa3b, v138
	v_fmamk_f32 v106, v106, 0x3e38aa3b, v139
	v_fmamk_f32 v75, v75, 0x3e38aa3b, v138
	v_fmamk_f32 v107, v107, 0x3e38aa3b, v139
	v_fmamk_f32 v76, v76, 0x3e38aa3b, v138
	v_fmamk_f32 v108, v108, 0x3e38aa3b, v139
	v_fmamk_f32 v77, v77, 0x3e38aa3b, v138
	v_fmamk_f32 v109, v109, 0x3e38aa3b, v139
	v_fmamk_f32 v78, v78, 0x3e38aa3b, v138
	v_fmamk_f32 v110, v110, 0x3e38aa3b, v139
	v_fmamk_f32 v79, v79, 0x3e38aa3b, v138
	v_fmamk_f32 v111, v111, 0x3e38aa3b, v139
	v_fmamk_f32 v80, v80, 0x3e38aa3b, v138
	v_fmamk_f32 v112, v112, 0x3e38aa3b, v139
	v_fmamk_f32 v81, v81, 0x3e38aa3b, v138
	v_fmamk_f32 v113, v113, 0x3e38aa3b, v139
	v_exp_f32_e32 v74, v74
	v_exp_f32_e32 v106, v106
	v_exp_f32_e32 v75, v75
	v_exp_f32_e32 v107, v107
	v_exp_f32_e32 v76, v76
	v_exp_f32_e32 v108, v108
	v_exp_f32_e32 v77, v77
	v_exp_f32_e32 v109, v109
	v_exp_f32_e32 v78, v78
	v_exp_f32_e32 v110, v110
	v_exp_f32_e32 v79, v79
	v_exp_f32_e32 v111, v111
	v_exp_f32_e32 v80, v80
	v_exp_f32_e32 v112, v112
	v_exp_f32_e32 v81, v81
	v_exp_f32_e32 v113, v113
	v_cvt_pk_bf16_f32 v66, v66, v67
	v_cvt_pk_bf16_f32 v98, v98, v99
	v_cvt_pk_bf16_f32 v67, v68, v69
	v_cvt_pk_bf16_f32 v99, v100, v101
	v_cvt_pk_bf16_f32 v68, v70, v71
	v_cvt_pk_bf16_f32 v100, v102, v103
	v_cvt_pk_bf16_f32 v69, v72, v73
	v_cvt_pk_bf16_f32 v101, v104, v105
	v_cvt_pk_bf16_f32 v74, v74, v75
	v_cvt_pk_bf16_f32 v106, v106, v107
	v_cvt_pk_bf16_f32 v75, v76, v77
	v_cvt_pk_bf16_f32 v107, v108, v109
	v_cvt_pk_bf16_f32 v76, v78, v79
	v_cvt_pk_bf16_f32 v108, v110, v111
	v_cvt_pk_bf16_f32 v77, v80, v81
	v_cvt_pk_bf16_f32 v109, v112, v113
	s_setprio 2
	ds_read_b128 v[86:89], v183 offset:9216
	ds_read_b128 v[94:97], v183 offset:13824
	ds_read_b128 v[70:73], v183 offset:9248
	ds_read_b128 v[78:81], v183 offset:13856
	ds_read_b128 v[118:121], v183 offset:9280
	ds_read_b128 v[126:129], v183 offset:13888
	ds_read_b128 v[102:105], v183 offset:9312
	ds_read_b128 v[110:113], v183 offset:13920
	s_waitcnt lgkmcnt(7)
; #define MFMA(a, b, c) __builtin_amdgcn_mfma_f32_32x32x16_bf16((a), (b), (c), 0, 0, 0)
; template <int DQK, bool BAND, int QT> ...
;     ...
;   for (int kt = kbeg; kt < kend; kt += 64, ++it) {
;     const char* st = lds + (it & 1) * ST;
;     const bool more = (kt + 64 < kend);
;     if (more) gload(kt + 64);
;     bool need = true;
;     if (BAND) need = (kt + 63 >= qw0 - 64) && (kt <= qw0 + WQ - 1 + 64);
;     if (need) {
;       f32x16 s[2][QT];
; #pragma unroll
;       for (int a = 0; a < 2; ++a)
; #pragma unroll
;         for (int b = 0; b < QT; ++b)
; #pragma unroll
;           for (int r = 0; r < 16; ++r) s[a][b][r] = 0.f;
; #pragma unroll
;       for (int ks = 0; ks < NKS; ++ks) {
;         const bf16x8 k0 = *(const bf16x8*)(st + k_rd + ks * 32);
;         const bf16x8 k1 = *(const bf16x8*)(st + k_rd + 32 * KROW + ks * 32);
; #pragma unroll
;         for (int qt = 0; qt < QT; ++qt) {
;           s[0][qt] = MFMA(k0, qf[qt][ks], s[0][qt]);
;           s[1][qt] = MFMA(k1, qf[qt][ks], s[1][qt]);
;         }
;       }
;     ...
; #pragma unroll
;       for (int ks = 0; ks < 4; ++ks) {
;         const bf16x8 v0 = *(const bf16x8*)(st + v_rd + ks * 32);
;         const bf16x8 v1 = *(const bf16x8*)(st + v_rd + 32 * LROW + ks * 32);
; #pragma unroll
;         for (int qt = 0; qt < QT; ++qt) {
;           o[0][qt] = MFMA(v0, pf[qt][ks], o[0][qt]);
;           o[1][qt] = MFMA(v1, pf[qt][ks], o[1][qt]);
;         }
;       }
;     } else {
;       if (more) lstore(lds + ((it + 1) & 1) * ST);
;     }
;     __syncthreads();
;   }
	v_mfma_f32_32x32x16_bf16 v[50:65], v[86:89], v[82:85], v[50:65]
	v_mfma_f32_32x32x16_bf16 v[18:33], v[86:89], v[114:117], v[18:33]
	s_waitcnt lgkmcnt(6)
	v_mfma_f32_32x32x16_bf16 v[34:49], v[94:97], v[82:85], v[34:49]
	v_mfma_f32_32x32x16_bf16 v[2:17], v[94:97], v[114:117], v[2:17]
	v_mfma_f32_16x16x32_bf16 v[240:243], v[244:247], v[82:85], v[240:243]
	v_mfma_f32_16x16x32_bf16 v[236:239], v[244:247], v[114:117], v[236:239]
	s_waitcnt lgkmcnt(5)
	v_mfma_f32_32x32x16_bf16 v[50:65], v[70:73], v[90:93], v[50:65]
	v_mfma_f32_32x32x16_bf16 v[18:33], v[70:73], v[122:125], v[18:33]
	s_waitcnt lgkmcnt(4)
	v_mfma_f32_32x32x16_bf16 v[34:49], v[78:81], v[90:93], v[34:49]
	v_mfma_f32_32x32x16_bf16 v[2:17], v[78:81], v[122:125], v[2:17]
	v_mfma_f32_16x16x32_bf16 v[240:243], v[244:247], v[90:93], v[240:243]
	v_mfma_f32_16x16x32_bf16 v[236:239], v[244:247], v[122:125], v[236:239]
	s_waitcnt lgkmcnt(3)
	v_mfma_f32_32x32x16_bf16 v[50:65], v[118:121], v[66:69], v[50:65]
	v_mfma_f32_32x32x16_bf16 v[18:33], v[118:121], v[98:101], v[18:33]
	s_waitcnt lgkmcnt(2)
	v_mfma_f32_32x32x16_bf16 v[34:49], v[126:129], v[66:69], v[34:49]
	v_mfma_f32_32x32x16_bf16 v[2:17], v[126:129], v[98:101], v[2:17]
	v_mfma_f32_16x16x32_bf16 v[240:243], v[244:247], v[66:69], v[240:243]
	v_mfma_f32_16x16x32_bf16 v[236:239], v[244:247], v[98:101], v[236:239]
	s_nop 0
	s_add_i32 s1, s1, 1
	s_add_i32 s6, s6, 64
	s_waitcnt vmcnt(0) lgkmcnt(0)
	s_barrier
	v_mfma_f32_32x32x16_bf16 v[50:65], v[102:105], v[74:77], v[50:65]
	v_mfma_f32_32x32x16_bf16 v[18:33], v[102:105], v[106:109], v[18:33]
	v_mfma_f32_32x32x16_bf16 v[34:49], v[110:113], v[74:77], v[34:49]
	v_mfma_f32_32x32x16_bf16 v[2:17], v[110:113], v[106:109], v[2:17]
	v_mfma_f32_16x16x32_bf16 v[240:243], v[244:247], v[74:77], v[240:243]
	v_mfma_f32_16x16x32_bf16 v[236:239], v[244:247], v[106:109], v[236:239]
	s_cmp_lg_u32 s21, s1
	s_cbranch_scc0 .Lgqa_u2exit
	s_nop 0
.Lgqa_topb:
	ds_read_b128 v[206:209], v140
	ds_read_b128 v[210:213], v140 offset:4608
	ds_read_b128 v[214:217], v140 offset:32
	ds_read_b128 v[232:235], v140 offset:4640
	s_waitcnt lgkmcnt(3)
	v_mfma_f32_32x32x16_bf16 v[82:97], v[206:209], v[146:149], 0
	v_mfma_f32_32x32x16_bf16 v[114:129], v[206:209], v[162:165], 0
	ds_read_b128 v[206:209], v140 offset:64
	s_waitcnt lgkmcnt(3)
	v_mfma_f32_32x32x16_bf16 v[66:81], v[210:213], v[146:149], 0
	v_mfma_f32_32x32x16_bf16 v[98:113], v[210:213], v[162:165], 0
	ds_read_b128 v[210:213], v140 offset:4672
	s_waitcnt lgkmcnt(3)
	v_mfma_f32_32x32x16_bf16 v[82:97], v[214:217], v[150:153], v[82:97]
	v_mfma_f32_32x32x16_bf16 v[114:129], v[214:217], v[166:169], v[114:129]
	ds_read_b128 v[214:217], v140 offset:96
	s_waitcnt lgkmcnt(3)
	v_mfma_f32_32x32x16_bf16 v[66:81], v[232:235], v[150:153], v[66:81]
	v_mfma_f32_32x32x16_bf16 v[98:113], v[232:235], v[166:169], v[98:113]
	ds_read_b128 v[232:235], v140 offset:4704
	s_waitcnt lgkmcnt(3)
	v_mfma_f32_32x32x16_bf16 v[82:97], v[206:209], v[154:157], v[82:97]
	v_mfma_f32_32x32x16_bf16 v[114:129], v[206:209], v[170:173], v[114:129]
	s_waitcnt lgkmcnt(2)
	v_mfma_f32_32x32x16_bf16 v[66:81], v[210:213], v[154:157], v[66:81]
	v_mfma_f32_32x32x16_bf16 v[98:113], v[210:213], v[170:173], v[98:113]
	s_waitcnt lgkmcnt(1)
	v_mfma_f32_32x32x16_bf16 v[82:97], v[214:217], v[158:161], v[82:97]
	v_mfma_f32_32x32x16_bf16 v[114:129], v[214:217], v[174:177], v[114:129]
	s_waitcnt lgkmcnt(0)
	v_mfma_f32_32x32x16_bf16 v[66:81], v[232:235], v[158:161], v[66:81]
	v_mfma_f32_32x32x16_bf16 v[98:113], v[232:235], v[174:177], v[98:113]
	s_cmp_lt_u32 s6, s19
	s_cbranch_scc0 .Lgqab_dma_noload
	s_mov_b32 s2, s39
	s_nop 0
	s_nop 0
	s_mov_b32 m0, s2
	s_add_u32 s3, s2, 0x1000
	global_load_lds_dwordx4 v130, s[34:35]
	s_mov_b32 m0, s3
	s_add_u32 s3, s2, 0x2400
	global_load_lds_dwordx4 v131, s[34:35]
	s_mov_b32 m0, s3
	s_add_u32 s3, s2, 0x3400
	global_load_lds_dwordx4 v132, s[26:27]
	s_mov_b32 m0, s3
	s_sub_u32 s3, s2, s39
	global_load_lds_dwordx4 v133, s[26:27]
	s_cmp_gt_u32 s38, 1
	s_cbranch_scc1 .Lgqab_dma_x2
	s_cmp_eq_u32 s38, 0
	s_cbranch_scc0 .Lgqab_dma_x1
	s_add_u32 m0, s3, 0x2000
	s_nop 0
	global_load_lds_dwordx4 v134, s[34:35]
	s_branch .Lgqab_dma_x2

; #define MFMA(a, b, c) __builtin_amdgcn_mfma_f32_32x32x16_bf16((a), (b), (c), 0, 0, 0)
; DI unsigned pk2(float a, float b) { f32x2 v = {a, b}; bf16x2_t r = __builtin_convertvector(v, bf16x2_t); return __builtin_bit_cast(unsigned, r); }
; template <int DQK, bool BAND, int QT> ...
;     ...
;         const float mc = -m[qt] * cc;
;         float ls = 0.f;
; #pragma unroll
;         for (int a = 0; a < 2; ++a) {
; #pragma unroll
;           for (int r = 0; r < 16; ++r) { const float pv = __builtin_amdgcn_exp2f(fmaf(s[a][qt][r], cc, mc)); s[a][qt][r] = pv; ls += pv; }
; #pragma unroll
;           for (int s2 = 0; s2 < 2; ++s2) {
;             u32x4 pk;
;             pk.x = pk2(s[a][qt][8 * s2 + 0], s[a][qt][8 * s2 + 1]);
;             pk.y = pk2(s[a][qt][8 * s2 + 2], s[a][qt][8 * s2 + 3]);
;             pk.z = pk2(s[a][qt][8 * s2 + 4], s[a][qt][8 * s2 + 5]);
;             pk.w = pk2(s[a][qt][8 * s2 + 6], s[a][qt][8 * s2 + 7]);
;             pf[qt][a * 2 + s2] = __builtin_bit_cast(bf16x8, pk);
;           }
;         }
;         l[qt] += ls;
;       }
;       __builtin_amdgcn_s_setprio(0);
;       if (more) lstore(lds + ((it + 1) & 1) * ST);
; #pragma unroll
;       for (int ks = 0; ks < 4; ++ks) {
;         const bf16x8 v0 = *(const bf16x8*)(st + v_rd + ks * 32);
;         const bf16x8 v1 = *(const bf16x8*)(st + v_rd + 32 * LROW + ks * 32);
; #pragma unroll
;         for (int qt = 0; qt < QT; ++qt) {
;           o[0][qt] = MFMA(v0, pf[qt][ks], o[0][qt]);
;           o[1][qt] = MFMA(v1, pf[qt][ks], o[1][qt]);
;         }
;       }
.Lgqab_nr1:
	v_fmamk_f32 v82, v82, 0x3e38aa3b, v138
	v_fmamk_f32 v114, v114, 0x3e38aa3b, v139
	v_fmamk_f32 v83, v83, 0x3e38aa3b, v138
	v_fmamk_f32 v115, v115, 0x3e38aa3b, v139
	v_fmamk_f32 v84, v84, 0x3e38aa3b, v138
	v_fmamk_f32 v116, v116, 0x3e38aa3b, v139
	v_fmamk_f32 v85, v85, 0x3e38aa3b, v138
	v_fmamk_f32 v117, v117, 0x3e38aa3b, v139
	v_fmamk_f32 v86, v86, 0x3e38aa3b, v138
	v_fmamk_f32 v118, v118, 0x3e38aa3b, v139
	v_fmamk_f32 v87, v87, 0x3e38aa3b, v138
	v_fmamk_f32 v119, v119, 0x3e38aa3b, v139
	v_fmamk_f32 v88, v88, 0x3e38aa3b, v138
	v_fmamk_f32 v120, v120, 0x3e38aa3b, v139
	v_fmamk_f32 v89, v89, 0x3e38aa3b, v138
	v_fmamk_f32 v121, v121, 0x3e38aa3b, v139
	v_exp_f32_e32 v82, v82
	v_exp_f32_e32 v114, v114
	v_exp_f32_e32 v83, v83
	v_exp_f32_e32 v115, v115
	v_exp_f32_e32 v84, v84
	v_exp_f32_e32 v116, v116
	v_exp_f32_e32 v85, v85
	v_exp_f32_e32 v117, v117
	v_exp_f32_e32 v86, v86
	v_exp_f32_e32 v118, v118
	v_exp_f32_e32 v87, v87
	v_exp_f32_e32 v119, v119
	v_exp_f32_e32 v88, v88
	v_exp_f32_e32 v120, v120
	v_exp_f32_e32 v89, v89
	v_exp_f32_e32 v121, v121
	v_fmamk_f32 v90, v90, 0x3e38aa3b, v138
	v_fmamk_f32 v122, v122, 0x3e38aa3b, v139
	v_fmamk_f32 v91, v91, 0x3e38aa3b, v138
	v_fmamk_f32 v123, v123, 0x3e38aa3b, v139
	v_fmamk_f32 v92, v92, 0x3e38aa3b, v138
	v_fmamk_f32 v124, v124, 0x3e38aa3b, v139
	v_fmamk_f32 v93, v93, 0x3e38aa3b, v138
	v_fmamk_f32 v125, v125, 0x3e38aa3b, v139
	v_fmamk_f32 v94, v94, 0x3e38aa3b, v138
	v_fmamk_f32 v126, v126, 0x3e38aa3b, v139
	v_fmamk_f32 v95, v95, 0x3e38aa3b, v138
	v_fmamk_f32 v127, v127, 0x3e38aa3b, v139
	v_fmamk_f32 v96, v96, 0x3e38aa3b, v138
	v_fmamk_f32 v128, v128, 0x3e38aa3b, v139
	v_fmamk_f32 v97, v97, 0x3e38aa3b, v138
	v_fmamk_f32 v129, v129, 0x3e38aa3b, v139
	v_exp_f32_e32 v90, v90
	v_exp_f32_e32 v122, v122
	v_exp_f32_e32 v91, v91
	v_exp_f32_e32 v123, v123
	v_exp_f32_e32 v92, v92
	v_exp_f32_e32 v124, v124
	v_exp_f32_e32 v93, v93
	v_exp_f32_e32 v125, v125
	v_exp_f32_e32 v94, v94
	v_exp_f32_e32 v126, v126
	v_exp_f32_e32 v95, v95
	v_exp_f32_e32 v127, v127
	v_exp_f32_e32 v96, v96
	v_exp_f32_e32 v128, v128
	v_exp_f32_e32 v97, v97
	v_exp_f32_e32 v129, v129
	v_cvt_pk_bf16_f32 v82, v82, v83
	v_cvt_pk_bf16_f32 v114, v114, v115
	v_cvt_pk_bf16_f32 v83, v84, v85
	v_cvt_pk_bf16_f32 v115, v116, v117
	v_cvt_pk_bf16_f32 v84, v86, v87
	v_cvt_pk_bf16_f32 v116, v118, v119
	v_cvt_pk_bf16_f32 v85, v88, v89
	v_cvt_pk_bf16_f32 v117, v120, v121
	v_fmamk_f32 v66, v66, 0x3e38aa3b, v138
	v_fmamk_f32 v98, v98, 0x3e38aa3b, v139
	v_fmamk_f32 v67, v67, 0x3e38aa3b, v138
	v_fmamk_f32 v99, v99, 0x3e38aa3b, v139
	v_fmamk_f32 v68, v68, 0x3e38aa3b, v138
	v_fmamk_f32 v100, v100, 0x3e38aa3b, v139
	v_fmamk_f32 v69, v69, 0x3e38aa3b, v138
	v_fmamk_f32 v101, v101, 0x3e38aa3b, v139
	v_fmamk_f32 v70, v70, 0x3e38aa3b, v138
	v_fmamk_f32 v102, v102, 0x3e38aa3b, v139
	v_fmamk_f32 v71, v71, 0x3e38aa3b, v138
	v_fmamk_f32 v103, v103, 0x3e38aa3b, v139
	v_fmamk_f32 v72, v72, 0x3e38aa3b, v138
	v_fmamk_f32 v104, v104, 0x3e38aa3b, v139
	v_fmamk_f32 v73, v73, 0x3e38aa3b, v138
	v_fmamk_f32 v105, v105, 0x3e38aa3b, v139
	v_exp_f32_e32 v66, v66
	v_exp_f32_e32 v98, v98
	v_exp_f32_e32 v67, v67
	v_exp_f32_e32 v99, v99
	v_exp_f32_e32 v68, v68
	v_exp_f32_e32 v100, v100
	v_exp_f32_e32 v69, v69
	v_exp_f32_e32 v101, v101
	v_exp_f32_e32 v70, v70
	v_exp_f32_e32 v102, v102
	v_exp_f32_e32 v71, v71
	v_exp_f32_e32 v103, v103
	v_exp_f32_e32 v72, v72
	v_exp_f32_e32 v104, v104
	v_exp_f32_e32 v73, v73
	v_exp_f32_e32 v105, v105
	v_cvt_pk_bf16_f32 v90, v90, v91
	v_cvt_pk_bf16_f32 v122, v122, v123
	v_cvt_pk_bf16_f32 v91, v92, v93
	v_cvt_pk_bf16_f32 v123, v124, v125
	v_cvt_pk_bf16_f32 v92, v94, v95
	v_cvt_pk_bf16_f32 v124, v126, v127
	v_cvt_pk_bf16_f32 v93, v96, v97
	v_cvt_pk_bf16_f32 v125, v128, v129
	v_fmamk_f32 v74, v74, 0x3e38aa3b, v138
	v_fmamk_f32 v106, v106, 0x3e38aa3b, v139
	v_fmamk_f32 v75, v75, 0x3e38aa3b, v138
	v_fmamk_f32 v107, v107, 0x3e38aa3b, v139
	v_fmamk_f32 v76, v76, 0x3e38aa3b, v138
	v_fmamk_f32 v108, v108, 0x3e38aa3b, v139
	v_fmamk_f32 v77, v77, 0x3e38aa3b, v138
	v_fmamk_f32 v109, v109, 0x3e38aa3b, v139
	v_fmamk_f32 v78, v78, 0x3e38aa3b, v138
	v_fmamk_f32 v110, v110, 0x3e38aa3b, v139
	v_fmamk_f32 v79, v79, 0x3e38aa3b, v138
	v_fmamk_f32 v111, v111, 0x3e38aa3b, v139
	v_fmamk_f32 v80, v80, 0x3e38aa3b, v138
	v_fmamk_f32 v112, v112, 0x3e38aa3b, v139
	v_fmamk_f32 v81, v81, 0x3e38aa3b, v138
	v_fmamk_f32 v113, v113, 0x3e38aa3b, v139
	v_exp_f32_e32 v74, v74
	v_exp_f32_e32 v106, v106
	v_exp_f32_e32 v75, v75
	v_exp_f32_e32 v107, v107
	v_exp_f32_e32 v76, v76
	v_exp_f32_e32 v108, v108
	v_exp_f32_e32 v77, v77
	v_exp_f32_e32 v109, v109
	v_exp_f32_e32 v78, v78
	v_exp_f32_e32 v110, v110
	v_exp_f32_e32 v79, v79
	v_exp_f32_e32 v111, v111
	v_exp_f32_e32 v80, v80
	v_exp_f32_e32 v112, v112
	v_exp_f32_e32 v81, v81
	v_exp_f32_e32 v113, v113
	v_cvt_pk_bf16_f32 v66, v66, v67
	v_cvt_pk_bf16_f32 v98, v98, v99
	v_cvt_pk_bf16_f32 v67, v68, v69
	v_cvt_pk_bf16_f32 v99, v100, v101
	v_cvt_pk_bf16_f32 v68, v70, v71
	v_cvt_pk_bf16_f32 v100, v102, v103
	v_cvt_pk_bf16_f32 v69, v72, v73
	v_cvt_pk_bf16_f32 v101, v104, v105
	v_cvt_pk_bf16_f32 v74, v74, v75
	v_cvt_pk_bf16_f32 v106, v106, v107
	v_cvt_pk_bf16_f32 v75, v76, v77
	v_cvt_pk_bf16_f32 v107, v108, v109
	v_cvt_pk_bf16_f32 v76, v78, v79
	v_cvt_pk_bf16_f32 v108, v110, v111
	v_cvt_pk_bf16_f32 v77, v80, v81
	v_cvt_pk_bf16_f32 v109, v112, v113
	s_setprio 2
	ds_read_b128 v[86:89], v141 offset:9216
	ds_read_b128 v[94:97], v141 offset:13824
	ds_read_b128 v[70:73], v141 offset:9248
	ds_read_b128 v[78:81], v141 offset:13856
	ds_read_b128 v[118:121], v141 offset:9280
	ds_read_b128 v[126:129], v141 offset:13888
	ds_read_b128 v[102:105], v141 offset:9312
	ds_read_b128 v[110:113], v141 offset:13920
	s_waitcnt lgkmcnt(7)
; #define MFMA(a, b, c) __builtin_amdgcn_mfma_f32_32x32x16_bf16((a), (b), (c), 0, 0, 0)
; template <int DQK, bool BAND, int QT> ...
;     ...
; #pragma unroll
;       for (int ks = 0; ks < 4; ++ks) {
;         const bf16x8 v0 = *(const bf16x8*)(st + v_rd + ks * 32);
;         const bf16x8 v1 = *(const bf16x8*)(st + v_rd + 32 * LROW + ks * 32);
; #pragma unroll
;         for (int qt = 0; qt < QT; ++qt) {
;           o[0][qt] = MFMA(v0, pf[qt][ks], o[0][qt]);
;           o[1][qt] = MFMA(v1, pf[qt][ks], o[1][qt]);
;         }
;       }
;     } else {
;       if (more) lstore(lds + ((it + 1) & 1) * ST);
;     }
;     __syncthreads();
;   }
; #pragma unroll
;   for (int qt = 0; qt < QT; ++qt) {
;     const float lt = l[qt] + __shfl_xor(l[qt], 32);
	v_mfma_f32_32x32x16_bf16 v[50:65], v[86:89], v[82:85], v[50:65]
	v_mfma_f32_32x32x16_bf16 v[18:33], v[86:89], v[114:117], v[18:33]
	s_waitcnt lgkmcnt(6)
	v_mfma_f32_32x32x16_bf16 v[34:49], v[94:97], v[82:85], v[34:49]
	v_mfma_f32_32x32x16_bf16 v[2:17], v[94:97], v[114:117], v[2:17]
	v_mfma_f32_16x16x32_bf16 v[240:243], v[244:247], v[82:85], v[240:243]
	v_mfma_f32_16x16x32_bf16 v[236:239], v[244:247], v[114:117], v[236:239]
	s_waitcnt lgkmcnt(5)
	v_mfma_f32_32x32x16_bf16 v[50:65], v[70:73], v[90:93], v[50:65]
	v_mfma_f32_32x32x16_bf16 v[18:33], v[70:73], v[122:125], v[18:33]
	s_waitcnt lgkmcnt(4)
	v_mfma_f32_32x32x16_bf16 v[34:49], v[78:81], v[90:93], v[34:49]
	v_mfma_f32_32x32x16_bf16 v[2:17], v[78:81], v[122:125], v[2:17]
	v_mfma_f32_16x16x32_bf16 v[240:243], v[244:247], v[90:93], v[240:243]
	v_mfma_f32_16x16x32_bf16 v[236:239], v[244:247], v[122:125], v[236:239]
	s_waitcnt lgkmcnt(3)
	v_mfma_f32_32x32x16_bf16 v[50:65], v[118:121], v[66:69], v[50:65]
	v_mfma_f32_32x32x16_bf16 v[18:33], v[118:121], v[98:101], v[18:33]
	s_waitcnt lgkmcnt(2)
	v_mfma_f32_32x32x16_bf16 v[34:49], v[126:129], v[66:69], v[34:49]
	v_mfma_f32_32x32x16_bf16 v[2:17], v[126:129], v[98:101], v[2:17]
	v_mfma_f32_16x16x32_bf16 v[240:243], v[244:247], v[66:69], v[240:243]
	v_mfma_f32_16x16x32_bf16 v[236:239], v[244:247], v[98:101], v[236:239]
	s_nop 0
	s_add_i32 s1, s1, 1
	s_add_i32 s6, s6, 64
	s_waitcnt vmcnt(0) lgkmcnt(0)
	s_barrier
	v_mfma_f32_32x32x16_bf16 v[50:65], v[102:105], v[74:77], v[50:65]
	v_mfma_f32_32x32x16_bf16 v[18:33], v[102:105], v[106:109], v[18:33]
	v_mfma_f32_32x32x16_bf16 v[34:49], v[110:113], v[74:77], v[34:49]
	v_mfma_f32_32x32x16_bf16 v[2:17], v[110:113], v[106:109], v[2:17]
	v_mfma_f32_16x16x32_bf16 v[240:243], v[244:247], v[74:77], v[240:243]
	v_mfma_f32_16x16x32_bf16 v[236:239], v[244:247], v[106:109], v[236:239]
	s_cmp_lg_u32 s21, s1
	s_cbranch_scc1 .Lgqa_top
.Lgqa_u2exit:
	s_setprio 0
	s_nop 7
	v_mbcnt_lo_u32_b32 v254, -1, 0
	v_mbcnt_hi_u32_b32 v254, -1, v254
	v_and_b32_e32 v255, 15, v254
	v_lshlrev_b32_e32 v255, 2, v255
	ds_bpermute_b32 v203, v255, v240
	ds_bpermute_b32 v253, v255, v241
	s_waitcnt lgkmcnt(0)
	v_cmp_gt_u32_e32 vcc, 16, v254
	s_nop 1
	v_cndmask_b32_e32 v187, v253, v203, vcc
	v_cmp_gt_u32_e32 vcc, 32, v254
	s_nop 1
	v_cndmask_b32_e32 v187, 0, v187, vcc
	ds_bpermute_b32 v203, v255, v236
	ds_bpermute_b32 v253, v255, v237
	s_waitcnt lgkmcnt(0)
	v_cmp_gt_u32_e32 vcc, 16, v254
	s_nop 1
	v_cndmask_b32_e32 v181, v253, v203, vcc
	v_cmp_gt_u32_e32 vcc, 32, v254
	s_nop 1
	v_cndmask_b32_e32 v181, 0, v181, vcc

; template <int DQK, bool BAND, int QT> ...
;     ...
;   const int tid = tid_(), lane = tid & 63, w = tid >> 6, h = lane >> 5, ql = lane & 31;
;   float* bias_l = (float*)(lds + 2 * ST);
;   if (BAND) { if (tid < 129) bias_l[tid] = bias_g[tid]; }
;   bf16x8 qf[QT][NKS];
; #pragma unroll
;   for (int qt = 0; qt < QT; ++qt)
; #pragma unroll
;     for (int ks = 0; ks < NKS; ++ks) qf[qt][ks] = *(const bf16x8*)(Q + (size_t)(w * WQ + qt * 32 + ql) * DQK + ks * 16 + h * 8);
;   f32x16 o[2][QT];
; #pragma unroll
;   for (int a = 0; a < 2; ++a)
; #pragma unroll
;     for (int b = 0; b < QT; ++b)
; #pragma unroll
;       for (int r = 0; r < 16; ++r) o[a][b][r] = 0.f;
;   float m[QT], l[QT];
; #pragma unroll
;   for (int qt = 0; qt < QT; ++qt) { m[qt] = -1e30f; l[qt] = 0.f; }
;   u32x4 rk[NKL], rv[2];
;   const int vrow0 = tid >> 3, vch = tid & 7;
;   unsigned klds[NKL];
; #pragma unroll
;   for (int i = 0; i < NKL; ++i) { const int idx = tid + i * 256, kr = idx / KV4, kc = idx - kr * KV4; klds[i] = kr * KROW + kc * 16; }
;   const unsigned koff0 = (unsigned)tid * 16u;
;   const unsigned voff0 = (unsigned)(vrow0 * ldv + vch * 8) * 2u, vstep = (unsigned)(32 * ldv) * 2u;
;   const unsigned vlds0 = KST + vrow0 * LROW + vch * 16;
;   auto gload = [&](int kt) {
;     const char* kb = (const char*)Kp + (size_t)kt * (DQK * 2);
;     const char* vb = (const char*)Vt + (size_t)kt * 2;
; #pragma unroll
;     for (int i = 0; i < NKL; ++i) rk[i] = *(const u32x4*)(kb + (koff0 + i * 4096u));
; #pragma unroll
; DI void phase_attn(const Ctx& c) {
;     ...
;     if (item < n_mla) {
;       const int hh = item & 7, rest = item >> 3, seq = rest / nqb, qb = rest - seq * nqb;
;       const size_t hs = (size_t)(seq * 8 + hh) * S;
;       if (ATT_PIPE) attn_dense<96>(wsb(c, OFF_QA) + (hs + qb * QBLK) * 96, wsb(c, OFF_KA) + hs * 96, wsb(c, OFF_VTA) + (size_t)(seq * 8 + hh) * 64 * (S + 64), S + 64,
;                      S, 0.10206207261596577f * LOG2E, wsb(c, OFF_OA) + ((size_t)seq * S + qb * QBLK) * LDO + hh * 64, LDO, c.lds);
;       else attn_item<96, false, AQT>(wsb(c, OFF_QA) + (hs + qb * QBLK) * 96, wsb(c, OFF_KA) + hs * 96, wsb(c, OFF_VTA) + (size_t)(seq * 8 + hh) * 64 * (S + 64), S + 64,
;                      0, S, 0, nullptr, 0.10206207261596577f * LOG2E, wsb(c, OFF_OA) + ((size_t)seq * S + qb * QBLK) * LDO + hh * 64, LDO, nullptr, 0, c.lds);
.LBB0_839:
	s_andn2_b64 vcc, exec, s[0:1]
	s_cbranch_vccnz .LBB0_664
	s_abs_i32 s0, s25
	v_readlane_b32 s1, v248, 3
	s_mul_hi_u32 s1, s0, s1
	v_readlane_b32 s4, v248, 2
	s_mul_i32 s2, s1, s4
	s_sub_i32 s0, s0, s2
	s_ashr_i32 s7, s25, 31
	s_add_i32 s2, s1, 1
	s_sub_i32 s3, s0, s4
	s_cmp_ge_u32 s0, s4
	s_cselect_b32 s1, s2, s1
	s_cselect_b32 s0, s3, s0
	s_add_i32 s2, s1, 1
	s_cmp_ge_u32 s0, s4
	s_cselect_b32 s0, s2, s1
	s_xor_b32 s38, s0, s7
	s_sub_i32 s0, s38, s7
	s_lshl_b32 s1, s0, s60
	s_lshl_b32 s2, s0, 3
	v_readlane_b32 s40, v249, 31
	s_sub_i32 s1, s25, s1
	s_or_b32 s26, s2, s40
	s_ashr_i32 s27, s26, 31
	s_lshl_b32 s4, s1, 8
	s_lshl_b64 s[34:35], s[26:27], s20
	s_ashr_i32 s5, s4, 31
	s_add_u32 s1, s34, s4
	s_addc_u32 s2, s35, s5
	s_mulk_i32 s2, 0xc0
	s_mul_hi_u32 s3, s1, 0xc0
	s_add_i32 s3, s3, s2
	s_mulk_i32 s1, 0xc0
	v_readlane_b32 s42, v250, 40
	v_readlane_b32 s43, v250, 41
	s_add_u32 s2, s42, s1
	s_mul_i32 s1, s35, 0xc0
	s_mul_hi_u32 s6, s34, 0xc0
	s_addc_u32 s3, s43, s3
	s_add_i32 s25, s6, s1
	s_mul_i32 s39, s34, 0xc0
	v_readlane_b32 s34, v250, 38
	v_readlane_b32 s35, v250, 39
	s_add_u32 s34, s34, s39
	v_mov_b32_e32 v2, v199
	s_addc_u32 s35, s35, s25
	v_readlane_b32 s1, v249, 61
	v_lshlrev_b32_e32 v4, 4, v2
	global_load_dwordx4 v[130:133], v4, s[34:35]
	v_add_u32_e32 v8, 0x1000, v4
	global_load_dwordx4 v[134:137], v8, s[34:35]
	s_mul_hi_i32 s27, s26, s1
	s_mul_i32 s26, s26, s1
	s_lshl_b64 s[26:27], s[26:27], 1
	v_readlane_b32 s42, v250, 36
	v_ashrrev_i32_e32 v3, 3, v2
	v_readlane_b32 s6, v249, 63
	v_readlane_b32 s43, v250, 37
	s_add_u32 s26, s42, s26
	v_and_b32_e32 v6, 0x70, v4
	v_mul_lo_u32 v0, v3, s6
	s_addc_u32 s27, s43, s27
	v_add_u32_e32 v10, 0x2000, v4
	v_or_b32_e32 v12, v6, v0
	v_bfe_u32 v230, v2, 5, 1
	global_load_dwordx4 v[138:141], v10, s[34:35]
	v_add_u32_e32 v14, s1, v12
	global_load_dwordx4 v[146:149], v12, s[26:27]
	global_load_dwordx4 v[170:173], v14, s[26:27]
	v_lshlrev_b32_e32 v0, 4, v230
	v_and_b32_e32 v204, 0xffffffdf, v2
	v_lshl_add_u64 v[16:17], s[2:3], 0, v[0:1]
	s_movk_i32 s1, 0xc0
	v_or_b32_e32 v202, 32, v2
	v_mad_i64_i32 v[18:19], s[2:3], v204, s1, v[16:17]
	v_mad_i64_i32 v[16:17], s[2:3], v202, s1, v[16:17]
	global_load_dwordx4 v[142:145], v[18:19], off
	global_load_dwordx4 v[150:153], v[18:19], off offset:32
	global_load_dwordx4 v[154:157], v[18:19], off offset:64
	global_load_dwordx4 v[158:161], v[18:19], off offset:96
	global_load_dwordx4 v[162:165], v[18:19], off offset:128
	global_load_dwordx4 v[166:169], v[18:19], off offset:160
	global_load_dwordx4 v[174:177], v[16:17], off
	global_load_dwordx4 v[178:181], v[16:17], off offset:32
	global_load_dwordx4 v[182:185], v[16:17], off offset:64
	global_load_dwordx4 v[186:189], v[16:17], off offset:96
	global_load_dwordx4 v[190:193], v[16:17], off offset:128
	global_load_dwordx4 v[194:197], v[16:17], off offset:160
	s_mov_b32 s1, 0x2aaaaaab
	v_mul_hi_i32 v5, v2, s1
	v_lshrrev_b32_e32 v7, 31, v5
	v_ashrrev_i32_e32 v5, 1, v5
	v_add_u32_e32 v5, v5, v7
	s_movk_i32 s6, 0xd0
	v_mad_u64_u32 v[16:17], s[2:3], v5, -12, v[2:3]
	v_mul_lo_u32 v5, v5, s6
	v_lshl_add_u32 v231, v16, 4, v5
	v_add_u32_e32 v16, 0x100, v2
	v_mul_hi_i32 v5, v16, s1
	v_lshrrev_b32_e32 v7, 31, v5
	v_ashrrev_i32_e32 v5, 1, v5
	v_add_u32_e32 v5, v5, v7
	v_mad_u64_u32 v[16:17], s[2:3], v5, -12, v[16:17]
	v_mul_lo_u32 v5, v5, s6
	v_lshl_add_u32 v232, v16, 4, v5
	v_add_u32_e32 v16, 0x200, v2
	v_mul_hi_i32 v5, v16, s1
	v_lshrrev_b32_e32 v7, 31, v5
	v_ashrrev_i32_e32 v5, 1, v5
	v_add_u32_e32 v5, v5, v7
	v_mad_u64_u32 v[16:17], s[2:3], v5, -12, v[16:17]
	v_mul_lo_u32 v5, v5, s6
	v_add_u32_e32 v7, 0, v231
	v_lshl_add_u32 v233, v16, 4, v5
	v_mov_b32_e32 v13, v1
	v_mov_b32_e32 v15, v1
	v_cmp_lt_i32_e32 vcc, v221, v220
	v_mov_b32_e32 v5, v1
	v_mov_b32_e32 v9, v1
	v_mov_b32_e32 v11, v1
	v_mov_b32_e32 v50, v1
	v_mov_b32_e32 v51, v1
	v_mov_b32_e32 v52, v1
	v_mov_b32_e32 v53, v1
	v_mov_b32_e32 v54, v1
	v_mov_b32_e32 v55, v1
	v_mov_b32_e32 v56, v1
	v_mov_b32_e32 v57, v1
	v_mov_b32_e32 v58, v1
	v_mov_b32_e32 v59, v1
	v_mov_b32_e32 v60, v1
	v_mov_b32_e32 v61, v1
	v_mov_b32_e32 v62, v1
	v_mov_b32_e32 v63, v1
	s_waitcnt vmcnt(16)
	ds_write_b128 v7, v[130:133]
	v_add_u32_e32 v7, 0, v232
	s_waitcnt vmcnt(15)
	ds_write_b128 v7, v[134:137]
	v_add_u32_e32 v7, 0, v233
	v_mad_u64_u32 v[206:207], s[2:3], v3, s16, v[6:7]
	s_lshl_b32 s2, s38, 3
	s_or_b32 s2, s40, s2
	s_lshl_b32 s3, s7, 3
	v_add_u32_e32 v3, 0, v206
	s_sub_i32 s2, s2, s3
	v_readlane_b32 s7, v248, 4
	s_mul_hi_i32 s3, s7, s2
	s_mul_i32 s2, s7, s2
	v_lshlrev_b32_e32 v6, 1, v2
	s_add_u32 s2, s2, 0x10d35980
	v_and_b32_e32 v6, 8, v6
	s_waitcnt vmcnt(14)
	ds_write_b128 v7, v[138:141]
	s_waitcnt vmcnt(13)
	ds_write_b128 v3, v[146:149] offset:13312
	s_waitcnt vmcnt(12)
; template <int DQK, bool BAND, int QT> ...
;     ...
;   f32x16 o[2][QT];
; #pragma unroll
;   for (int a = 0; a < 2; ++a)
; #pragma unroll
;     for (int b = 0; b < QT; ++b)
; #pragma unroll
;       for (int r = 0; r < 16; ++r) o[a][b][r] = 0.f;
;   float m[QT], l[QT];
; #pragma unroll
;   for (int qt = 0; qt < QT; ++qt) { m[qt] = -1e30f; l[qt] = 0.f; }
;   u32x4 rk[NKL], rv[2];
;   const int vrow0 = tid >> 3, vch = tid & 7;
;   unsigned klds[NKL];
; #pragma unroll
;   for (int i = 0; i < NKL; ++i) { const int idx = tid + i * 256, kr = idx / KV4, kc = idx - kr * KV4; klds[i] = kr * KROW + kc * 16; }
;   const unsigned koff0 = (unsigned)tid * 16u;
;   const unsigned voff0 = (unsigned)(vrow0 * ldv + vch * 8) * 2u, vstep = (unsigned)(32 * ldv) * 2u;
;   const unsigned vlds0 = KST + vrow0 * LROW + vch * 16;
;   auto gload = [&](int kt) {
;     const char* kb = (const char*)Kp + (size_t)kt * (DQK * 2);
;     const char* vb = (const char*)Vt + (size_t)kt * 2;
; #pragma unroll
;     for (int i = 0; i < NKL; ++i) rk[i] = *(const u32x4*)(kb + (koff0 + i * 4096u));
; #pragma unroll
;     for (int i = 0; i < 2; ++i) rv[i] = *(const u32x4*)(vb + (voff0 + i * vstep));
;   };
;   auto lstore = [&](char* st) {
; #pragma unroll
;     for (int i = 0; i < NKL; ++i) *(u32x4*)(st + klds[i]) = rk[i];
; #pragma unroll
;     for (int i = 0; i < 2; ++i) *(u32x4*)(st + vlds0 + i * 32 * LROW) = rv[i];
;   };
;   gload(kbeg);
;   lstore(lds);
;   __syncthreads();
;   const int pr = (ql & ~12) | ((ql & 4) << 1) | ((ql & 8) >> 1);
;   const int k_rd = pr * KROW + h * 16;
;   const int v_rd = KST + ql * LROW + h * 16;
;   const int qw0 = q0 + w * WQ;
	ds_write_b128 v3, v[170:173] offset:17920
	v_and_b32_e32 v3, 31, v2
	v_mul_u32_u24_e32 v234, 0x90, v3
	v_and_b32_e32 v3, 19, v2
	v_lshrrev_b32_e32 v2, 1, v2
	v_and_b32_e32 v2, 4, v2
	s_addc_u32 s3, s3, 0
	v_or3_b32 v2, v3, v6, v2
	v_lshl_add_u64 v[208:209], s[2:3], 0, v[12:13]
	v_lshl_add_u64 v[210:211], s[2:3], 0, v[14:15]
	s_add_u32 s2, s39, 0xf538900
	v_mul_u32_u24_e32 v235, 0xd0, v2
	v_cndmask_b32_e32 v2, v219, v221, vcc
	s_addc_u32 s3, s25, 0
	v_lshlrev_b32_e32 v203, 2, v2
	v_lshl_add_u64 v[212:213], s[2:3], 0, v[4:5]
	v_lshl_add_u64 v[214:215], s[2:3], 0, v[8:9]
	v_lshl_add_u64 v[216:217], s[2:3], 0, v[10:11]
	v_mov_b32_e32 v64, v1
	v_mov_b32_e32 v65, v1
	v_mov_b64_e32 v[18:19], v[50:51]
	v_mov_b64_e32 v[34:35], v[50:51]
	v_mov_b64_e32 v[2:3], v[50:51]
	s_mov_b32 s1, 0
	s_mov_b32 s6, 64
	v_mov_b32_e32 v237, 0xf149f2ca
	v_mov_b32_e32 v236, 0
	v_mov_b32_e32 v207, 0
	v_mov_b32_e32 v238, 0xf149f2ca
	v_mov_b64_e32 v[20:21], v[52:53]
	v_mov_b64_e32 v[22:23], v[54:55]
	v_mov_b64_e32 v[24:25], v[56:57]
	v_mov_b64_e32 v[26:27], v[58:59]
	v_mov_b64_e32 v[28:29], v[60:61]
	v_mov_b64_e32 v[30:31], v[62:63]
	v_mov_b64_e32 v[32:33], v[64:65]
	v_mov_b64_e32 v[36:37], v[52:53]
	v_mov_b64_e32 v[38:39], v[54:55]
	v_mov_b64_e32 v[40:41], v[56:57]
	v_mov_b64_e32 v[42:43], v[58:59]
	v_mov_b64_e32 v[44:45], v[60:61]
	v_mov_b64_e32 v[46:47], v[62:63]
	v_mov_b64_e32 v[48:49], v[64:65]
	v_mov_b64_e32 v[4:5], v[52:53]
	v_mov_b64_e32 v[6:7], v[54:55]
	v_mov_b64_e32 v[8:9], v[56:57]
	v_mov_b64_e32 v[10:11], v[58:59]
	v_mov_b64_e32 v[12:13], v[60:61]
	v_mov_b64_e32 v[14:15], v[62:63]
	v_mov_b64_e32 v[16:17], v[64:65]
	v_add_u32_e32 v235, v235, v0
	v_add_u32_e32 v234, v234, v0
	v_mbcnt_lo_u32_b32 v254, -1, 0
	v_mbcnt_hi_u32_b32 v254, -1, v254
	v_and_b32_e32 v255, 15, v254
	v_lshrrev_b32_e32 v253, 4, v254
	v_and_b32_e32 v253, 1, v253
	v_cmp_eq_u32_e32 vcc, v255, v253
	v_mov_b32_e32 v253, 0x3f803f80
	s_nop 1
	v_cndmask_b32_e32 v130, 0, v253, vcc
	v_mov_b32_e32 v131, v130
	v_mov_b32_e32 v132, v130
	v_mov_b32_e32 v133, v130
	v_mov_b32_e32 v134, 0
	v_mov_b32_e32 v135, 0
	v_mov_b32_e32 v136, 0
	v_mov_b32_e32 v137, 0
	v_mov_b32_e32 v138, 0
	v_mov_b32_e32 v139, 0
	v_mov_b32_e32 v140, 0
	v_mov_b32_e32 v141, 0
	v_readfirstlane_b32 s38, v199
	s_lshr_b32 s38, s38, 6
	s_lshl_b32 s39, s38, 10
	v_readlane_b32 s25, v249, 63
	v_mov_b32_e32 v253, v199
	v_mul_u32_u24_e32 v254, 0x13b2, v253
	v_lshrrev_b32_e32 v254, 16, v254
	v_mul_u32_u24_e32 v255, 13, v254
	v_sub_u32_e32 v255, v253, v255
	v_min_u32_e32 v255, 11, v255
	v_mul_u32_u24_e32 v254, 0xc0, v254
	v_lshl_add_u32 v146, v255, 4, v254
	v_add_u32_e32 v253, 0x100, v199
	v_mul_u32_u24_e32 v254, 0x13b2, v253
	v_lshrrev_b32_e32 v254, 16, v254
	v_mul_u32_u24_e32 v255, 13, v254
	v_sub_u32_e32 v255, v253, v255
	v_min_u32_e32 v255, 11, v255
	v_mul_u32_u24_e32 v254, 0xc0, v254
	v_lshl_add_u32 v147, v255, 4, v254
	v_add_u32_e32 v253, 0x200, v199
	v_mul_u32_u24_e32 v254, 0x13b2, v253
	v_lshrrev_b32_e32 v254, 16, v254
	v_mul_u32_u24_e32 v255, 13, v254
	v_sub_u32_e32 v255, v253, v255
	v_min_u32_e32 v255, 11, v255
	v_mul_u32_u24_e32 v254, 0xc0, v254
	v_lshl_add_u32 v148, v255, 4, v254
	v_mov_b32_e32 v253, v199
	v_mul_u32_u24_e32 v254, 0x1c72, v253
	v_lshrrev_b32_e32 v254, 16, v254
	v_mul_u32_u24_e32 v255, 9, v254
	v_sub_u32_e32 v255, v253, v255
	v_min_u32_e32 v255, 7, v255
	v_mul_lo_u32 v254, v254, s25
	v_lshl_add_u32 v170, v255, 4, v254
	v_add_u32_e32 v253, 0x100, v199
	v_mul_u32_u24_e32 v254, 0x1c72, v253
	v_lshrrev_b32_e32 v254, 16, v254
	v_mul_u32_u24_e32 v255, 9, v254
	v_sub_u32_e32 v255, v253, v255
	v_min_u32_e32 v255, 7, v255
	v_mul_lo_u32 v254, v254, s25
	v_lshl_add_u32 v171, v255, 4, v254
	v_add_u32_e32 v253, 0x300, v199
	v_mul_u32_u24_e32 v254, 0x13b2, v253
	v_lshrrev_b32_e32 v254, 16, v254
	v_mul_u32_u24_e32 v255, 13, v254
	v_sub_u32_e32 v255, v253, v255
	v_min_u32_e32 v255, 11, v255
	v_mul_u32_u24_e32 v254, 0xc0, v254
	v_lshl_add_u32 v149, v255, 4, v254
	v_add_u32_e32 v253, 0x1c0, v199
	v_mul_u32_u24_e32 v254, 0x1c72, v253
	v_lshrrev_b32_e32 v254, 16, v254
	v_mul_u32_u24_e32 v255, 9, v254
	v_sub_u32_e32 v255, v253, v255
	v_min_u32_e32 v255, 7, v255
	v_mul_lo_u32 v254, v254, s25
	v_lshl_add_u32 v172, v255, 4, v254
	v_cmp_gt_u32_e32 vcc, 64, v199
	s_nop 1
	v_cndmask_b32_e32 v149, v172, v149, vcc
	v_readfirstlane_b32 s34, v212
	v_readfirstlane_b32 s35, v213
	s_add_u32 s34, s34, s94
	s_addc_u32 s35, s35, s95
	s_sub_u32 s34, s34, s39
	s_subb_u32 s35, s35, 0
	v_readfirstlane_b32 s26, v208
	v_readfirstlane_b32 s27, v209
	s_add_u32 s26, s26, s94
	s_addc_u32 s27, s27, s95
	s_mul_i32 s42, s38, s25
	s_lshl_b32 s42, s42, 3
	s_sub_u32 s26, s26, s42
	s_subb_u32 s27, s27, 0
	v_mov_b32_e32 v208, 0xf149f2ca
	v_mov_b32_e32 v209, 0xf149f2ca
	v_mov_b32_e32 v210, 0
	v_mov_b32_e32 v211, 0
	v_add_u32_e32 v172, 0x5800, v235
	v_add_u32_e32 v173, 0x5800, v234
	s_waitcnt vmcnt(0) lgkmcnt(0)
	s_barrier
; #define MFMA(a, b, c) __builtin_amdgcn_mfma_f32_32x32x16_bf16((a), (b), (c), 0, 0, 0)
; template <int DQK, bool BAND, int QT> ...
;     ...
;   for (int kt = kbeg; kt < kend; kt += 64, ++it) {
;     const char* st = lds + (it & 1) * ST;
;     const bool more = (kt + 64 < kend);
;     if (more) gload(kt + 64);
;     bool need = true;
;     if (BAND) need = (kt + 63 >= qw0 - 64) && (kt <= qw0 + WQ - 1 + 64);
;     if (need) {
;       f32x16 s[2][QT];
; #pragma unroll
;       for (int a = 0; a < 2; ++a)
; #pragma unroll
;         for (int b = 0; b < QT; ++b)
; #pragma unroll
;           for (int r = 0; r < 16; ++r) s[a][b][r] = 0.f;
; #pragma unroll
;       for (int ks = 0; ks < NKS; ++ks) {
;         const bf16x8 k0 = *(const bf16x8*)(st + k_rd + ks * 32);
;         const bf16x8 k1 = *(const bf16x8*)(st + k_rd + 32 * KROW + ks * 32);
; #pragma unroll
;         for (int qt = 0; qt < QT; ++qt) {
;           s[0][qt] = MFMA(k0, qf[qt][ks], s[0][qt]);
;           s[1][qt] = MFMA(k1, qf[qt][ks], s[1][qt]);
;         }
;       }
.Lmla_top:
	ds_read_b128 v[102:105], v235
	ds_read_b128 v[98:101], v235 offset:6656
	ds_read_b128 v[240:243], v235 offset:32
	ds_read_b128 v[244:247], v235 offset:6688
	s_waitcnt lgkmcnt(3)
	v_mfma_f32_32x32x16_bf16 v[82:97], v[102:105], v[142:145], 0
	v_mfma_f32_32x32x16_bf16 v[114:129], v[102:105], v[174:177], 0
	s_waitcnt lgkmcnt(2)
	v_mfma_f32_32x32x16_bf16 v[66:81], v[98:101], v[142:145], 0
	v_mfma_f32_32x32x16_bf16 v[98:113], v[98:101], v[174:177], 0
	s_waitcnt lgkmcnt(1)
	v_mfma_f32_32x32x16_bf16 v[82:97], v[240:243], v[150:153], v[82:97]
	v_mfma_f32_32x32x16_bf16 v[114:129], v[240:243], v[178:181], v[114:129]
	ds_read_b128 v[240:243], v235 offset:64
	s_waitcnt lgkmcnt(1)
	v_mfma_f32_32x32x16_bf16 v[66:81], v[244:247], v[150:153], v[66:81]
	v_mfma_f32_32x32x16_bf16 v[98:113], v[244:247], v[178:181], v[98:113]
	ds_read_b128 v[244:247], v235 offset:6720
	s_waitcnt lgkmcnt(1)
	v_mfma_f32_32x32x16_bf16 v[82:97], v[240:243], v[154:157], v[82:97]
	v_mfma_f32_32x32x16_bf16 v[114:129], v[240:243], v[182:185], v[114:129]
	ds_read_b128 v[240:243], v235 offset:96
	s_waitcnt lgkmcnt(1)
	v_mfma_f32_32x32x16_bf16 v[66:81], v[244:247], v[154:157], v[66:81]
	v_mfma_f32_32x32x16_bf16 v[98:113], v[244:247], v[182:185], v[98:113]
	ds_read_b128 v[244:247], v235 offset:6752
	s_waitcnt lgkmcnt(1)
	v_mfma_f32_32x32x16_bf16 v[82:97], v[240:243], v[158:161], v[82:97]
	v_mfma_f32_32x32x16_bf16 v[114:129], v[240:243], v[186:189], v[114:129]
	ds_read_b128 v[240:243], v235 offset:128
	s_waitcnt lgkmcnt(1)
	v_mfma_f32_32x32x16_bf16 v[66:81], v[244:247], v[158:161], v[66:81]
	v_mfma_f32_32x32x16_bf16 v[98:113], v[244:247], v[186:189], v[98:113]
	ds_read_b128 v[244:247], v235 offset:6784
	s_waitcnt lgkmcnt(1)
	v_mfma_f32_32x32x16_bf16 v[82:97], v[240:243], v[162:165], v[82:97]
	v_mfma_f32_32x32x16_bf16 v[114:129], v[240:243], v[190:193], v[114:129]
	ds_read_b128 v[240:243], v235 offset:160
	s_waitcnt lgkmcnt(1)
	v_mfma_f32_32x32x16_bf16 v[66:81], v[244:247], v[162:165], v[66:81]
	v_mfma_f32_32x32x16_bf16 v[98:113], v[244:247], v[190:193], v[98:113]
	ds_read_b128 v[244:247], v235 offset:6816
	s_waitcnt lgkmcnt(1)
	v_mfma_f32_32x32x16_bf16 v[82:97], v[240:243], v[166:169], v[82:97]
	v_mfma_f32_32x32x16_bf16 v[114:129], v[240:243], v[194:197], v[114:129]
	s_waitcnt lgkmcnt(0)
	v_mfma_f32_32x32x16_bf16 v[66:81], v[244:247], v[166:169], v[66:81]
	v_mfma_f32_32x32x16_bf16 v[98:113], v[244:247], v[194:197], v[98:113]
	s_cmp_lt_u32 s6, s19
	s_cbranch_scc0 .Lmla_dma_noload
	s_add_u32 s2, s39, 0x5800
	s_nop 0
	s_mov_b32 m0, s2
	s_add_u32 s3, s2, 0x1000
	global_load_lds_dwordx4 v146, s[34:35]
	s_mov_b32 m0, s3
	s_add_u32 s3, s2, 0x2000
	global_load_lds_dwordx4 v147, s[34:35]
	s_mov_b32 m0, s3
	s_add_u32 s3, s2, 0x3400
	global_load_lds_dwordx4 v148, s[34:35]
	s_mov_b32 m0, s3
	s_add_u32 s3, s2, 0x4400
	global_load_lds_dwordx4 v170, s[26:27]
	s_mov_b32 m0, s3
	s_sub_u32 s3, s2, s39
	global_load_lds_dwordx4 v171, s[26:27]
	s_cmp_gt_u32 s38, 1
	s_cbranch_scc1 .Lmla_dma_x2
	s_cmp_eq_u32 s38, 0
	s_cbranch_scc0 .Lmla_dma_x1
	s_add_u32 m0, s3, 0x3000
	s_nop 0
	global_load_lds_dwordx4 v149, s[34:35]
	s_branch .Lmla_dma_x2

; #define MFMA(a, b, c) __builtin_amdgcn_mfma_f32_32x32x16_bf16((a), (b), (c), 0, 0, 0)
; DI unsigned pk2(float a, float b) { f32x2 v = {a, b}; bf16x2_t r = __builtin_convertvector(v, bf16x2_t); return __builtin_bit_cast(unsigned, r); }
; template <int DQK, bool BAND, int QT> ...
;     ...
;         const float mc = -m[qt] * cc;
;         float ls = 0.f;
; #pragma unroll
;         for (int a = 0; a < 2; ++a) {
; #pragma unroll
;           for (int r = 0; r < 16; ++r) { const float pv = __builtin_amdgcn_exp2f(fmaf(s[a][qt][r], cc, mc)); s[a][qt][r] = pv; ls += pv; }
; #pragma unroll
;           for (int s2 = 0; s2 < 2; ++s2) {
;             u32x4 pk;
;             pk.x = pk2(s[a][qt][8 * s2 + 0], s[a][qt][8 * s2 + 1]);
;             pk.y = pk2(s[a][qt][8 * s2 + 2], s[a][qt][8 * s2 + 3]);
;             pk.z = pk2(s[a][qt][8 * s2 + 4], s[a][qt][8 * s2 + 5]);
;             pk.w = pk2(s[a][qt][8 * s2 + 6], s[a][qt][8 * s2 + 7]);
;             pf[qt][a * 2 + s2] = __builtin_bit_cast(bf16x8, pk);
;           }
;         }
;         l[qt] += ls;
;       }
;       __builtin_amdgcn_s_setprio(0);
;       if (more) lstore(lds + ((it + 1) & 1) * ST);
; #pragma unroll
;       for (int ks = 0; ks < 4; ++ks) {
;         const bf16x8 v0 = *(const bf16x8*)(st + v_rd + ks * 32);
;         const bf16x8 v1 = *(const bf16x8*)(st + v_rd + 32 * LROW + ks * 32);
; #pragma unroll
;         for (int qt = 0; qt < QT; ++qt) {
;           o[0][qt] = MFMA(v0, pf[qt][ks], o[0][qt]);
;           o[1][qt] = MFMA(v1, pf[qt][ks], o[1][qt]);
;         }
;       }
.Lmla_nr1:
	v_fmamk_f32 v82, v82, 0x3e16c740, v210
	v_fmamk_f32 v114, v114, 0x3e16c740, v211
	v_fmamk_f32 v83, v83, 0x3e16c740, v210
	v_fmamk_f32 v115, v115, 0x3e16c740, v211
	v_fmamk_f32 v84, v84, 0x3e16c740, v210
	v_fmamk_f32 v116, v116, 0x3e16c740, v211
	v_fmamk_f32 v85, v85, 0x3e16c740, v210
	v_fmamk_f32 v117, v117, 0x3e16c740, v211
	v_fmamk_f32 v86, v86, 0x3e16c740, v210
	v_fmamk_f32 v118, v118, 0x3e16c740, v211
	v_fmamk_f32 v87, v87, 0x3e16c740, v210
	v_fmamk_f32 v119, v119, 0x3e16c740, v211
	v_fmamk_f32 v88, v88, 0x3e16c740, v210
	v_fmamk_f32 v120, v120, 0x3e16c740, v211
	v_fmamk_f32 v89, v89, 0x3e16c740, v210
	v_fmamk_f32 v121, v121, 0x3e16c740, v211
	v_exp_f32_e32 v82, v82
	v_exp_f32_e32 v114, v114
	v_exp_f32_e32 v83, v83
	v_exp_f32_e32 v115, v115
	v_exp_f32_e32 v84, v84
	v_exp_f32_e32 v116, v116
	v_exp_f32_e32 v85, v85
	v_exp_f32_e32 v117, v117
	v_exp_f32_e32 v86, v86
	v_exp_f32_e32 v118, v118
	v_exp_f32_e32 v87, v87
	v_exp_f32_e32 v119, v119
	v_exp_f32_e32 v88, v88
	v_exp_f32_e32 v120, v120
	v_exp_f32_e32 v89, v89
	v_exp_f32_e32 v121, v121
	v_fmamk_f32 v90, v90, 0x3e16c740, v210
	v_fmamk_f32 v122, v122, 0x3e16c740, v211
	v_fmamk_f32 v91, v91, 0x3e16c740, v210
	v_fmamk_f32 v123, v123, 0x3e16c740, v211
	v_fmamk_f32 v92, v92, 0x3e16c740, v210
	v_fmamk_f32 v124, v124, 0x3e16c740, v211
	v_fmamk_f32 v93, v93, 0x3e16c740, v210
	v_fmamk_f32 v125, v125, 0x3e16c740, v211
	v_fmamk_f32 v94, v94, 0x3e16c740, v210
	v_fmamk_f32 v126, v126, 0x3e16c740, v211
	v_fmamk_f32 v95, v95, 0x3e16c740, v210
	v_fmamk_f32 v127, v127, 0x3e16c740, v211
	v_fmamk_f32 v96, v96, 0x3e16c740, v210
	v_fmamk_f32 v128, v128, 0x3e16c740, v211
	v_fmamk_f32 v97, v97, 0x3e16c740, v210
	v_fmamk_f32 v129, v129, 0x3e16c740, v211
	v_exp_f32_e32 v90, v90
	v_exp_f32_e32 v122, v122
	v_exp_f32_e32 v91, v91
	v_exp_f32_e32 v123, v123
	v_exp_f32_e32 v92, v92
	v_exp_f32_e32 v124, v124
	v_exp_f32_e32 v93, v93
	v_exp_f32_e32 v125, v125
	v_exp_f32_e32 v94, v94
	v_exp_f32_e32 v126, v126
	v_exp_f32_e32 v95, v95
	v_exp_f32_e32 v127, v127
	v_exp_f32_e32 v96, v96
	v_exp_f32_e32 v128, v128
	v_exp_f32_e32 v97, v97
	v_exp_f32_e32 v129, v129
	v_cvt_pk_bf16_f32 v82, v82, v83
	v_cvt_pk_bf16_f32 v114, v114, v115
	v_cvt_pk_bf16_f32 v83, v84, v85
	v_cvt_pk_bf16_f32 v115, v116, v117
	v_cvt_pk_bf16_f32 v84, v86, v87
	v_cvt_pk_bf16_f32 v116, v118, v119
	v_cvt_pk_bf16_f32 v85, v88, v89
	v_cvt_pk_bf16_f32 v117, v120, v121
	v_fmamk_f32 v66, v66, 0x3e16c740, v210
	v_fmamk_f32 v98, v98, 0x3e16c740, v211
	v_fmamk_f32 v67, v67, 0x3e16c740, v210
	v_fmamk_f32 v99, v99, 0x3e16c740, v211
	v_fmamk_f32 v68, v68, 0x3e16c740, v210
	v_fmamk_f32 v100, v100, 0x3e16c740, v211
	v_fmamk_f32 v69, v69, 0x3e16c740, v210
	v_fmamk_f32 v101, v101, 0x3e16c740, v211
	v_fmamk_f32 v70, v70, 0x3e16c740, v210
	v_fmamk_f32 v102, v102, 0x3e16c740, v211
	v_fmamk_f32 v71, v71, 0x3e16c740, v210
	v_fmamk_f32 v103, v103, 0x3e16c740, v211
	v_fmamk_f32 v72, v72, 0x3e16c740, v210
	v_fmamk_f32 v104, v104, 0x3e16c740, v211
	v_fmamk_f32 v73, v73, 0x3e16c740, v210
	v_fmamk_f32 v105, v105, 0x3e16c740, v211
	v_exp_f32_e32 v66, v66
	v_exp_f32_e32 v98, v98
	v_exp_f32_e32 v67, v67
	v_exp_f32_e32 v99, v99
	v_exp_f32_e32 v68, v68
	v_exp_f32_e32 v100, v100
	v_exp_f32_e32 v69, v69
	v_exp_f32_e32 v101, v101
	v_exp_f32_e32 v70, v70
	v_exp_f32_e32 v102, v102
	v_exp_f32_e32 v71, v71
	v_exp_f32_e32 v103, v103
	v_exp_f32_e32 v72, v72
	v_exp_f32_e32 v104, v104
	v_exp_f32_e32 v73, v73
	v_exp_f32_e32 v105, v105
	v_cvt_pk_bf16_f32 v90, v90, v91
	v_cvt_pk_bf16_f32 v122, v122, v123
	v_cvt_pk_bf16_f32 v91, v92, v93
	v_cvt_pk_bf16_f32 v123, v124, v125
	v_cvt_pk_bf16_f32 v92, v94, v95
	v_cvt_pk_bf16_f32 v124, v126, v127
	v_cvt_pk_bf16_f32 v93, v96, v97
	v_cvt_pk_bf16_f32 v125, v128, v129
	v_fmamk_f32 v74, v74, 0x3e16c740, v210
	v_fmamk_f32 v106, v106, 0x3e16c740, v211
	v_fmamk_f32 v75, v75, 0x3e16c740, v210
	v_fmamk_f32 v107, v107, 0x3e16c740, v211
	v_fmamk_f32 v76, v76, 0x3e16c740, v210
	v_fmamk_f32 v108, v108, 0x3e16c740, v211
	v_fmamk_f32 v77, v77, 0x3e16c740, v210
	v_fmamk_f32 v109, v109, 0x3e16c740, v211
	v_fmamk_f32 v78, v78, 0x3e16c740, v210
	v_fmamk_f32 v110, v110, 0x3e16c740, v211
	v_fmamk_f32 v79, v79, 0x3e16c740, v210
	v_fmamk_f32 v111, v111, 0x3e16c740, v211
	v_fmamk_f32 v80, v80, 0x3e16c740, v210
	v_fmamk_f32 v112, v112, 0x3e16c740, v211
	v_fmamk_f32 v81, v81, 0x3e16c740, v210
	v_fmamk_f32 v113, v113, 0x3e16c740, v211
	v_exp_f32_e32 v74, v74
	v_exp_f32_e32 v106, v106
	v_exp_f32_e32 v75, v75
	v_exp_f32_e32 v107, v107
	v_exp_f32_e32 v76, v76
	v_exp_f32_e32 v108, v108
	v_exp_f32_e32 v77, v77
	v_exp_f32_e32 v109, v109
	v_exp_f32_e32 v78, v78
	v_exp_f32_e32 v110, v110
	v_exp_f32_e32 v79, v79
	v_exp_f32_e32 v111, v111
	v_exp_f32_e32 v80, v80
	v_exp_f32_e32 v112, v112
	v_exp_f32_e32 v81, v81
	v_exp_f32_e32 v113, v113
	v_cvt_pk_bf16_f32 v66, v66, v67
	v_cvt_pk_bf16_f32 v98, v98, v99
	v_cvt_pk_bf16_f32 v67, v68, v69
	v_cvt_pk_bf16_f32 v99, v100, v101
	v_cvt_pk_bf16_f32 v68, v70, v71
	v_cvt_pk_bf16_f32 v100, v102, v103
	v_cvt_pk_bf16_f32 v69, v72, v73
	v_cvt_pk_bf16_f32 v101, v104, v105
	v_cvt_pk_bf16_f32 v74, v74, v75
	v_cvt_pk_bf16_f32 v106, v106, v107
	v_cvt_pk_bf16_f32 v75, v76, v77
	v_cvt_pk_bf16_f32 v107, v108, v109
	v_cvt_pk_bf16_f32 v76, v78, v79
	v_cvt_pk_bf16_f32 v108, v110, v111
	v_cvt_pk_bf16_f32 v77, v80, v81
	v_cvt_pk_bf16_f32 v109, v112, v113
	s_setprio 2
	ds_read_b128 v[86:89], v234 offset:13312
	ds_read_b128 v[94:97], v234 offset:17920
	ds_read_b128 v[70:73], v234 offset:13344
	ds_read_b128 v[78:81], v234 offset:17952
	ds_read_b128 v[118:121], v234 offset:13376
	ds_read_b128 v[126:129], v234 offset:17984
	ds_read_b128 v[102:105], v234 offset:13408
	ds_read_b128 v[110:113], v234 offset:18016
	s_waitcnt lgkmcnt(7)
; #define MFMA(a, b, c) __builtin_amdgcn_mfma_f32_32x32x16_bf16((a), (b), (c), 0, 0, 0)
; template <int DQK, bool BAND, int QT> ...
;     ...
;   for (int kt = kbeg; kt < kend; kt += 64, ++it) {
;     const char* st = lds + (it & 1) * ST;
;     const bool more = (kt + 64 < kend);
;     if (more) gload(kt + 64);
;     bool need = true;
;     if (BAND) need = (kt + 63 >= qw0 - 64) && (kt <= qw0 + WQ - 1 + 64);
;     if (need) {
;       f32x16 s[2][QT];
; #pragma unroll
;       for (int a = 0; a < 2; ++a)
; #pragma unroll
;         for (int b = 0; b < QT; ++b)
; #pragma unroll
;           for (int r = 0; r < 16; ++r) s[a][b][r] = 0.f;
; #pragma unroll
;       for (int ks = 0; ks < NKS; ++ks) {
;         const bf16x8 k0 = *(const bf16x8*)(st + k_rd + ks * 32);
;         const bf16x8 k1 = *(const bf16x8*)(st + k_rd + 32 * KROW + ks * 32);
; #pragma unroll
;         for (int qt = 0; qt < QT; ++qt) {
;           s[0][qt] = MFMA(k0, qf[qt][ks], s[0][qt]);
;           s[1][qt] = MFMA(k1, qf[qt][ks], s[1][qt]);
;         }
;       }
;     ...
; #pragma unroll
;       for (int ks = 0; ks < 4; ++ks) {
;         const bf16x8 v0 = *(const bf16x8*)(st + v_rd + ks * 32);
;         const bf16x8 v1 = *(const bf16x8*)(st + v_rd + 32 * LROW + ks * 32);
; #pragma unroll
;         for (int qt = 0; qt < QT; ++qt) {
;           o[0][qt] = MFMA(v0, pf[qt][ks], o[0][qt]);
;           o[1][qt] = MFMA(v1, pf[qt][ks], o[1][qt]);
;         }
;       }
;     } else {
;       if (more) lstore(lds + ((it + 1) & 1) * ST);
;     }
;     __syncthreads();
	v_mfma_f32_32x32x16_bf16 v[50:65], v[86:89], v[82:85], v[50:65]
	v_mfma_f32_32x32x16_bf16 v[18:33], v[86:89], v[114:117], v[18:33]
	s_waitcnt lgkmcnt(6)
	v_mfma_f32_32x32x16_bf16 v[34:49], v[94:97], v[82:85], v[34:49]
	v_mfma_f32_32x32x16_bf16 v[2:17], v[94:97], v[114:117], v[2:17]
	v_mfma_f32_16x16x32_bf16 v[134:137], v[130:133], v[82:85], v[134:137]
	v_mfma_f32_16x16x32_bf16 v[138:141], v[130:133], v[114:117], v[138:141]
	s_waitcnt lgkmcnt(5)
	v_mfma_f32_32x32x16_bf16 v[50:65], v[70:73], v[90:93], v[50:65]
	v_mfma_f32_32x32x16_bf16 v[18:33], v[70:73], v[122:125], v[18:33]
	s_waitcnt lgkmcnt(4)
	v_mfma_f32_32x32x16_bf16 v[34:49], v[78:81], v[90:93], v[34:49]
	v_mfma_f32_32x32x16_bf16 v[2:17], v[78:81], v[122:125], v[2:17]
	v_mfma_f32_16x16x32_bf16 v[134:137], v[130:133], v[90:93], v[134:137]
	v_mfma_f32_16x16x32_bf16 v[138:141], v[130:133], v[122:125], v[138:141]
	s_waitcnt lgkmcnt(3)
	v_mfma_f32_32x32x16_bf16 v[50:65], v[118:121], v[66:69], v[50:65]
	v_mfma_f32_32x32x16_bf16 v[18:33], v[118:121], v[98:101], v[18:33]
	s_waitcnt lgkmcnt(2)
	v_mfma_f32_32x32x16_bf16 v[34:49], v[126:129], v[66:69], v[34:49]
	v_mfma_f32_32x32x16_bf16 v[2:17], v[126:129], v[98:101], v[2:17]
	v_mfma_f32_16x16x32_bf16 v[134:137], v[130:133], v[66:69], v[134:137]
	v_mfma_f32_16x16x32_bf16 v[138:141], v[130:133], v[98:101], v[138:141]
	s_nop 0
	s_add_i32 s1, s1, 1
	s_add_i32 s6, s6, 64
	s_waitcnt vmcnt(0) lgkmcnt(0)
	s_barrier
	v_mfma_f32_32x32x16_bf16 v[50:65], v[102:105], v[74:77], v[50:65]
	v_mfma_f32_32x32x16_bf16 v[18:33], v[102:105], v[106:109], v[18:33]
	v_mfma_f32_32x32x16_bf16 v[34:49], v[110:113], v[74:77], v[34:49]
	v_mfma_f32_32x32x16_bf16 v[2:17], v[110:113], v[106:109], v[2:17]
	v_mfma_f32_16x16x32_bf16 v[134:137], v[130:133], v[74:77], v[134:137]
	v_mfma_f32_16x16x32_bf16 v[138:141], v[130:133], v[106:109], v[138:141]
	s_cmp_lg_u32 s21, s1
	s_cbranch_scc0 .Lmla_u2exit
.Lmla_topb:
	ds_read_b128 v[102:105], v172
	ds_read_b128 v[98:101], v172 offset:6656
	ds_read_b128 v[240:243], v172 offset:32
	ds_read_b128 v[244:247], v172 offset:6688
	s_waitcnt lgkmcnt(3)
	v_mfma_f32_32x32x16_bf16 v[82:97], v[102:105], v[142:145], 0
	v_mfma_f32_32x32x16_bf16 v[114:129], v[102:105], v[174:177], 0
	s_waitcnt lgkmcnt(2)
	v_mfma_f32_32x32x16_bf16 v[66:81], v[98:101], v[142:145], 0
	v_mfma_f32_32x32x16_bf16 v[98:113], v[98:101], v[174:177], 0
	s_waitcnt lgkmcnt(1)
	v_mfma_f32_32x32x16_bf16 v[82:97], v[240:243], v[150:153], v[82:97]
	v_mfma_f32_32x32x16_bf16 v[114:129], v[240:243], v[178:181], v[114:129]
	ds_read_b128 v[240:243], v172 offset:64
	s_waitcnt lgkmcnt(1)
	v_mfma_f32_32x32x16_bf16 v[66:81], v[244:247], v[150:153], v[66:81]
	v_mfma_f32_32x32x16_bf16 v[98:113], v[244:247], v[178:181], v[98:113]
	ds_read_b128 v[244:247], v172 offset:6720
	s_waitcnt lgkmcnt(1)
	v_mfma_f32_32x32x16_bf16 v[82:97], v[240:243], v[154:157], v[82:97]
	v_mfma_f32_32x32x16_bf16 v[114:129], v[240:243], v[182:185], v[114:129]
	ds_read_b128 v[240:243], v172 offset:96
	s_waitcnt lgkmcnt(1)
	v_mfma_f32_32x32x16_bf16 v[66:81], v[244:247], v[154:157], v[66:81]
	v_mfma_f32_32x32x16_bf16 v[98:113], v[244:247], v[182:185], v[98:113]
	ds_read_b128 v[244:247], v172 offset:6752
	s_waitcnt lgkmcnt(1)
	v_mfma_f32_32x32x16_bf16 v[82:97], v[240:243], v[158:161], v[82:97]
	v_mfma_f32_32x32x16_bf16 v[114:129], v[240:243], v[186:189], v[114:129]
	ds_read_b128 v[240:243], v172 offset:128
	s_waitcnt lgkmcnt(1)
	v_mfma_f32_32x32x16_bf16 v[66:81], v[244:247], v[158:161], v[66:81]
	v_mfma_f32_32x32x16_bf16 v[98:113], v[244:247], v[186:189], v[98:113]
	ds_read_b128 v[244:247], v172 offset:6784
	s_waitcnt lgkmcnt(1)
	v_mfma_f32_32x32x16_bf16 v[82:97], v[240:243], v[162:165], v[82:97]
	v_mfma_f32_32x32x16_bf16 v[114:129], v[240:243], v[190:193], v[114:129]
	ds_read_b128 v[240:243], v172 offset:160
	s_waitcnt lgkmcnt(1)
	v_mfma_f32_32x32x16_bf16 v[66:81], v[244:247], v[162:165], v[66:81]
	v_mfma_f32_32x32x16_bf16 v[98:113], v[244:247], v[190:193], v[98:113]
	ds_read_b128 v[244:247], v172 offset:6816
	s_waitcnt lgkmcnt(1)
	v_mfma_f32_32x32x16_bf16 v[82:97], v[240:243], v[166:169], v[82:97]
	v_mfma_f32_32x32x16_bf16 v[114:129], v[240:243], v[194:197], v[114:129]
	s_waitcnt lgkmcnt(0)
	v_mfma_f32_32x32x16_bf16 v[66:81], v[244:247], v[166:169], v[66:81]
	v_mfma_f32_32x32x16_bf16 v[98:113], v[244:247], v[194:197], v[98:113]
	s_cmp_lt_u32 s6, s19
	s_cbranch_scc0 .Lmlab_dma_noload
	s_mov_b32 s2, s39
	s_nop 0
	s_nop 0
	s_mov_b32 m0, s2
	s_add_u32 s3, s2, 0x1000
	global_load_lds_dwordx4 v146, s[34:35]
	s_mov_b32 m0, s3
	s_add_u32 s3, s2, 0x2000
	global_load_lds_dwordx4 v147, s[34:35]
	s_mov_b32 m0, s3
	s_add_u32 s3, s2, 0x3400
	global_load_lds_dwordx4 v148, s[34:35]
	s_mov_b32 m0, s3
	s_add_u32 s3, s2, 0x4400
	global_load_lds_dwordx4 v170, s[26:27]
	s_mov_b32 m0, s3
	s_sub_u32 s3, s2, s39
	global_load_lds_dwordx4 v171, s[26:27]
	s_cmp_gt_u32 s38, 1
	s_cbranch_scc1 .Lmlab_dma_x2
	s_cmp_eq_u32 s38, 0
	s_cbranch_scc0 .Lmlab_dma_x1
	s_add_u32 m0, s3, 0x3000
	s_nop 0
	global_load_lds_dwordx4 v149, s[34:35]
	s_branch .Lmlab_dma_x2

; DI unsigned pk2(float a, float b) { f32x2 v = {a, b}; bf16x2_t r = __builtin_convertvector(v, bf16x2_t); return __builtin_bit_cast(unsigned, r); }
; template <int DQK, bool BAND, int QT> ...
;     ...
;         const float mc = -m[qt] * cc;
;         float ls = 0.f;
; #pragma unroll
;         for (int a = 0; a < 2; ++a) {
; #pragma unroll
;           for (int r = 0; r < 16; ++r) { const float pv = __builtin_amdgcn_exp2f(fmaf(s[a][qt][r], cc, mc)); s[a][qt][r] = pv; ls += pv; }
; #pragma unroll
;           for (int s2 = 0; s2 < 2; ++s2) {
;             u32x4 pk;
;             pk.x = pk2(s[a][qt][8 * s2 + 0], s[a][qt][8 * s2 + 1]);
;             pk.y = pk2(s[a][qt][8 * s2 + 2], s[a][qt][8 * s2 + 3]);
;             pk.z = pk2(s[a][qt][8 * s2 + 4], s[a][qt][8 * s2 + 5]);
;             pk.w = pk2(s[a][qt][8 * s2 + 6], s[a][qt][8 * s2 + 7]);
;             pf[qt][a * 2 + s2] = __builtin_bit_cast(bf16x8, pk);
;           }
;         }
;         l[qt] += ls;
;       }
;       __builtin_amdgcn_s_setprio(0);
;       if (more) lstore(lds + ((it + 1) & 1) * ST);
; #pragma unroll
;       for (int ks = 0; ks < 4; ++ks) {
;         const bf16x8 v0 = *(const bf16x8*)(st + v_rd + ks * 32);
;         const bf16x8 v1 = *(const bf16x8*)(st + v_rd + 32 * LROW + ks * 32);
.Lmlab_nr1:
	v_fmamk_f32 v82, v82, 0x3e16c740, v210
	v_fmamk_f32 v114, v114, 0x3e16c740, v211
	v_fmamk_f32 v83, v83, 0x3e16c740, v210
	v_fmamk_f32 v115, v115, 0x3e16c740, v211
	v_fmamk_f32 v84, v84, 0x3e16c740, v210
	v_fmamk_f32 v116, v116, 0x3e16c740, v211
	v_fmamk_f32 v85, v85, 0x3e16c740, v210
	v_fmamk_f32 v117, v117, 0x3e16c740, v211
	v_fmamk_f32 v86, v86, 0x3e16c740, v210
	v_fmamk_f32 v118, v118, 0x3e16c740, v211
	v_fmamk_f32 v87, v87, 0x3e16c740, v210
	v_fmamk_f32 v119, v119, 0x3e16c740, v211
	v_fmamk_f32 v88, v88, 0x3e16c740, v210
	v_fmamk_f32 v120, v120, 0x3e16c740, v211
	v_fmamk_f32 v89, v89, 0x3e16c740, v210
	v_fmamk_f32 v121, v121, 0x3e16c740, v211
	v_exp_f32_e32 v82, v82
	v_exp_f32_e32 v114, v114
	v_exp_f32_e32 v83, v83
	v_exp_f32_e32 v115, v115
	v_exp_f32_e32 v84, v84
	v_exp_f32_e32 v116, v116
	v_exp_f32_e32 v85, v85
	v_exp_f32_e32 v117, v117
	v_exp_f32_e32 v86, v86
	v_exp_f32_e32 v118, v118
	v_exp_f32_e32 v87, v87
	v_exp_f32_e32 v119, v119
	v_exp_f32_e32 v88, v88
	v_exp_f32_e32 v120, v120
	v_exp_f32_e32 v89, v89
	v_exp_f32_e32 v121, v121
	v_fmamk_f32 v90, v90, 0x3e16c740, v210
	v_fmamk_f32 v122, v122, 0x3e16c740, v211
	v_fmamk_f32 v91, v91, 0x3e16c740, v210
	v_fmamk_f32 v123, v123, 0x3e16c740, v211
	v_fmamk_f32 v92, v92, 0x3e16c740, v210
	v_fmamk_f32 v124, v124, 0x3e16c740, v211
	v_fmamk_f32 v93, v93, 0x3e16c740, v210
	v_fmamk_f32 v125, v125, 0x3e16c740, v211
	v_fmamk_f32 v94, v94, 0x3e16c740, v210
	v_fmamk_f32 v126, v126, 0x3e16c740, v211
	v_fmamk_f32 v95, v95, 0x3e16c740, v210
	v_fmamk_f32 v127, v127, 0x3e16c740, v211
	v_fmamk_f32 v96, v96, 0x3e16c740, v210
	v_fmamk_f32 v128, v128, 0x3e16c740, v211
	v_fmamk_f32 v97, v97, 0x3e16c740, v210
	v_fmamk_f32 v129, v129, 0x3e16c740, v211
	v_exp_f32_e32 v90, v90
	v_exp_f32_e32 v122, v122
	v_exp_f32_e32 v91, v91
	v_exp_f32_e32 v123, v123
	v_exp_f32_e32 v92, v92
	v_exp_f32_e32 v124, v124
	v_exp_f32_e32 v93, v93
	v_exp_f32_e32 v125, v125
	v_exp_f32_e32 v94, v94
	v_exp_f32_e32 v126, v126
	v_exp_f32_e32 v95, v95
	v_exp_f32_e32 v127, v127
	v_exp_f32_e32 v96, v96
	v_exp_f32_e32 v128, v128
	v_exp_f32_e32 v97, v97
	v_exp_f32_e32 v129, v129
	v_cvt_pk_bf16_f32 v82, v82, v83
	v_cvt_pk_bf16_f32 v114, v114, v115
	v_cvt_pk_bf16_f32 v83, v84, v85
	v_cvt_pk_bf16_f32 v115, v116, v117
	v_cvt_pk_bf16_f32 v84, v86, v87
	v_cvt_pk_bf16_f32 v116, v118, v119
	v_cvt_pk_bf16_f32 v85, v88, v89
	v_cvt_pk_bf16_f32 v117, v120, v121
	v_fmamk_f32 v66, v66, 0x3e16c740, v210
	v_fmamk_f32 v98, v98, 0x3e16c740, v211
	v_fmamk_f32 v67, v67, 0x3e16c740, v210
	v_fmamk_f32 v99, v99, 0x3e16c740, v211
	v_fmamk_f32 v68, v68, 0x3e16c740, v210
	v_fmamk_f32 v100, v100, 0x3e16c740, v211
	v_fmamk_f32 v69, v69, 0x3e16c740, v210
	v_fmamk_f32 v101, v101, 0x3e16c740, v211
	v_fmamk_f32 v70, v70, 0x3e16c740, v210
	v_fmamk_f32 v102, v102, 0x3e16c740, v211
	v_fmamk_f32 v71, v71, 0x3e16c740, v210
	v_fmamk_f32 v103, v103, 0x3e16c740, v211
	v_fmamk_f32 v72, v72, 0x3e16c740, v210
	v_fmamk_f32 v104, v104, 0x3e16c740, v211
	v_fmamk_f32 v73, v73, 0x3e16c740, v210
	v_fmamk_f32 v105, v105, 0x3e16c740, v211
	v_exp_f32_e32 v66, v66
	v_exp_f32_e32 v98, v98
	v_exp_f32_e32 v67, v67
	v_exp_f32_e32 v99, v99
	v_exp_f32_e32 v68, v68
	v_exp_f32_e32 v100, v100
	v_exp_f32_e32 v69, v69
	v_exp_f32_e32 v101, v101
	v_exp_f32_e32 v70, v70
	v_exp_f32_e32 v102, v102
	v_exp_f32_e32 v71, v71
	v_exp_f32_e32 v103, v103
	v_exp_f32_e32 v72, v72
	v_exp_f32_e32 v104, v104
	v_exp_f32_e32 v73, v73
	v_exp_f32_e32 v105, v105
	v_cvt_pk_bf16_f32 v90, v90, v91
	v_cvt_pk_bf16_f32 v122, v122, v123
	v_cvt_pk_bf16_f32 v91, v92, v93
	v_cvt_pk_bf16_f32 v123, v124, v125
	v_cvt_pk_bf16_f32 v92, v94, v95
	v_cvt_pk_bf16_f32 v124, v126, v127
	v_cvt_pk_bf16_f32 v93, v96, v97
	v_cvt_pk_bf16_f32 v125, v128, v129
	v_fmamk_f32 v74, v74, 0x3e16c740, v210
	v_fmamk_f32 v106, v106, 0x3e16c740, v211
	v_fmamk_f32 v75, v75, 0x3e16c740, v210
	v_fmamk_f32 v107, v107, 0x3e16c740, v211
	v_fmamk_f32 v76, v76, 0x3e16c740, v210
	v_fmamk_f32 v108, v108, 0x3e16c740, v211
	v_fmamk_f32 v77, v77, 0x3e16c740, v210
	v_fmamk_f32 v109, v109, 0x3e16c740, v211
	v_fmamk_f32 v78, v78, 0x3e16c740, v210
	v_fmamk_f32 v110, v110, 0x3e16c740, v211
	v_fmamk_f32 v79, v79, 0x3e16c740, v210
	v_fmamk_f32 v111, v111, 0x3e16c740, v211
	v_fmamk_f32 v80, v80, 0x3e16c740, v210
	v_fmamk_f32 v112, v112, 0x3e16c740, v211
	v_fmamk_f32 v81, v81, 0x3e16c740, v210
	v_fmamk_f32 v113, v113, 0x3e16c740, v211
	v_exp_f32_e32 v74, v74
	v_exp_f32_e32 v106, v106
	v_exp_f32_e32 v75, v75
	v_exp_f32_e32 v107, v107
	v_exp_f32_e32 v76, v76
	v_exp_f32_e32 v108, v108
	v_exp_f32_e32 v77, v77
	v_exp_f32_e32 v109, v109
	v_exp_f32_e32 v78, v78
	v_exp_f32_e32 v110, v110
	v_exp_f32_e32 v79, v79
	v_exp_f32_e32 v111, v111
	v_exp_f32_e32 v80, v80
	v_exp_f32_e32 v112, v112
	v_exp_f32_e32 v81, v81
	v_exp_f32_e32 v113, v113
	v_cvt_pk_bf16_f32 v66, v66, v67
	v_cvt_pk_bf16_f32 v98, v98, v99
	v_cvt_pk_bf16_f32 v67, v68, v69
	v_cvt_pk_bf16_f32 v99, v100, v101
	v_cvt_pk_bf16_f32 v68, v70, v71
	v_cvt_pk_bf16_f32 v100, v102, v103
	v_cvt_pk_bf16_f32 v69, v72, v73
	v_cvt_pk_bf16_f32 v101, v104, v105
	v_cvt_pk_bf16_f32 v74, v74, v75
	v_cvt_pk_bf16_f32 v106, v106, v107
	v_cvt_pk_bf16_f32 v75, v76, v77
	v_cvt_pk_bf16_f32 v107, v108, v109
	v_cvt_pk_bf16_f32 v76, v78, v79
	v_cvt_pk_bf16_f32 v108, v110, v111
	v_cvt_pk_bf16_f32 v77, v80, v81
	v_cvt_pk_bf16_f32 v109, v112, v113
	s_setprio 2
	ds_read_b128 v[86:89], v173 offset:13312
	ds_read_b128 v[94:97], v173 offset:17920
	ds_read_b128 v[70:73], v173 offset:13344
	ds_read_b128 v[78:81], v173 offset:17952
	ds_read_b128 v[118:121], v173 offset:13376
	ds_read_b128 v[126:129], v173 offset:17984
	ds_read_b128 v[102:105], v173 offset:13408
	ds_read_b128 v[110:113], v173 offset:18016
	s_waitcnt lgkmcnt(7)
; #define MFMA(a, b, c) __builtin_amdgcn_mfma_f32_32x32x16_bf16((a), (b), (c), 0, 0, 0)
; template <int DQK, bool BAND, int QT> ...
;     ...
; #pragma unroll
;       for (int ks = 0; ks < 4; ++ks) {
;         const bf16x8 v0 = *(const bf16x8*)(st + v_rd + ks * 32);
;         const bf16x8 v1 = *(const bf16x8*)(st + v_rd + 32 * LROW + ks * 32);
; #pragma unroll
;         for (int qt = 0; qt < QT; ++qt) {
;           o[0][qt] = MFMA(v0, pf[qt][ks], o[0][qt]);
;           o[1][qt] = MFMA(v1, pf[qt][ks], o[1][qt]);
;         }
;       }
;     } else {
;       if (more) lstore(lds + ((it + 1) & 1) * ST);
;     }
;     __syncthreads();
;   }
; #pragma unroll
;   for (int qt = 0; qt < QT; ++qt) {
;     const float lt = l[qt] + __shfl_xor(l[qt], 32);
;     const float inv = __builtin_amdgcn_rcpf(lt);
	v_mfma_f32_32x32x16_bf16 v[50:65], v[86:89], v[82:85], v[50:65]
	v_mfma_f32_32x32x16_bf16 v[18:33], v[86:89], v[114:117], v[18:33]
	s_waitcnt lgkmcnt(6)
	v_mfma_f32_32x32x16_bf16 v[34:49], v[94:97], v[82:85], v[34:49]
	v_mfma_f32_32x32x16_bf16 v[2:17], v[94:97], v[114:117], v[2:17]
	v_mfma_f32_16x16x32_bf16 v[134:137], v[130:133], v[82:85], v[134:137]
	v_mfma_f32_16x16x32_bf16 v[138:141], v[130:133], v[114:117], v[138:141]
	s_waitcnt lgkmcnt(5)
	v_mfma_f32_32x32x16_bf16 v[50:65], v[70:73], v[90:93], v[50:65]
	v_mfma_f32_32x32x16_bf16 v[18:33], v[70:73], v[122:125], v[18:33]
	s_waitcnt lgkmcnt(4)
	v_mfma_f32_32x32x16_bf16 v[34:49], v[78:81], v[90:93], v[34:49]
	v_mfma_f32_32x32x16_bf16 v[2:17], v[78:81], v[122:125], v[2:17]
	v_mfma_f32_16x16x32_bf16 v[134:137], v[130:133], v[90:93], v[134:137]
	v_mfma_f32_16x16x32_bf16 v[138:141], v[130:133], v[122:125], v[138:141]
	s_waitcnt lgkmcnt(3)
	v_mfma_f32_32x32x16_bf16 v[50:65], v[118:121], v[66:69], v[50:65]
	v_mfma_f32_32x32x16_bf16 v[18:33], v[118:121], v[98:101], v[18:33]
	s_waitcnt lgkmcnt(2)
	v_mfma_f32_32x32x16_bf16 v[34:49], v[126:129], v[66:69], v[34:49]
	v_mfma_f32_32x32x16_bf16 v[2:17], v[126:129], v[98:101], v[2:17]
	v_mfma_f32_16x16x32_bf16 v[134:137], v[130:133], v[66:69], v[134:137]
	v_mfma_f32_16x16x32_bf16 v[138:141], v[130:133], v[98:101], v[138:141]
	s_nop 0
	s_add_i32 s1, s1, 1
	s_add_i32 s6, s6, 64
	s_waitcnt vmcnt(0) lgkmcnt(0)
	s_barrier
	v_mfma_f32_32x32x16_bf16 v[50:65], v[102:105], v[74:77], v[50:65]
	v_mfma_f32_32x32x16_bf16 v[18:33], v[102:105], v[106:109], v[18:33]
	v_mfma_f32_32x32x16_bf16 v[34:49], v[110:113], v[74:77], v[34:49]
	v_mfma_f32_32x32x16_bf16 v[2:17], v[110:113], v[106:109], v[2:17]
	v_mfma_f32_16x16x32_bf16 v[134:137], v[130:133], v[74:77], v[134:137]
	v_mfma_f32_16x16x32_bf16 v[138:141], v[130:133], v[106:109], v[138:141]
	s_cmp_lg_u32 s21, s1
	s_cbranch_scc1 .Lmla_top
.Lmla_u2exit:
	s_setprio 0
	s_nop 7
	v_mbcnt_lo_u32_b32 v254, -1, 0
	v_mbcnt_hi_u32_b32 v254, -1, v254
	v_and_b32_e32 v255, 15, v254
	v_lshlrev_b32_e32 v255, 2, v255
	ds_bpermute_b32 v239, v255, v134
	ds_bpermute_b32 v253, v255, v135
	s_waitcnt lgkmcnt(0)
	v_cmp_gt_u32_e32 vcc, 16, v254
	s_nop 1
	v_cndmask_b32_e32 v236, v253, v239, vcc
	v_cmp_gt_u32_e32 vcc, 32, v254
	s_nop 1
	v_cndmask_b32_e32 v236, 0, v236, vcc
	ds_bpermute_b32 v239, v255, v138
	ds_bpermute_b32 v253, v255, v139
	s_waitcnt lgkmcnt(0)
	v_cmp_gt_u32_e32 vcc, 16, v254
	s_nop 1
	v_cndmask_b32_e32 v207, v253, v239, vcc
	v_cmp_gt_u32_e32 vcc, 32, v254
	s_nop 1
	v_cndmask_b32_e32 v207, 0, v207, vcc
	s_branch .LBB0_663
	s_nop 0
